# stack on v73: prep first-section loads batched + rwkv_fin S_mid.z loop unrolled with prefetch + end-of-tile barriers removed + rotated GEMM k-loops
# speedup vs baseline: 1.0131x; 1.0045x over previous
; __device__ __forceinline__ void gemm_mainloop_d(const bf16_t* __restrict__ Ap, int lda, const bf16_t* __restrict__ Bt, int K,
;                                                 int m0, int n0, f32x4 (&acc)[4][4], char* lds) {
;     ...
;   for (int kt = 0; kt < nk; kt++) {
;     const int st = kt & 1;
;     if (kt + 1 < nk) dma(kt + 1, st ^ 1);
;     const char* la = lds + st * 32768; const char* lb = la + 16384;
;     bf16x8 af[2][4], bfv[2][4];
; #pragma unroll
;     for (int kc = 0; kc < 2; kc++) {
; #pragma unroll
;       for (int m = 0; m < 4; m++) { const int row = wr * 64 + m * 16 + fr; af[kc][m] = *(const bf16x8*)(la + (row * 8 + ((kc * 4 + fq) ^ ((row >> 1) & 7))) * 16); }
; #pragma unroll
;       for (int n = 0; n < 4; n++) { const int row = wc * 64 + n * 16 + fr; bfv[kc][n] = *(const bf16x8*)(lb + (row * 8 + ((kc * 4 + fq) ^ ((row >> 1) & 7))) * 16); }
;     }
;     __builtin_amdgcn_s_setprio(1);
; #pragma unroll
;     for (int kc = 0; kc < 2; kc++)
; #pragma unroll
;       for (int m = 0; m < 4; m++)
; #pragma unroll
;         for (int n = 0; n < 4; n++) acc[m][n] = __builtin_amdgcn_mfma_f32_16x16x32_bf16(bfv[kc][n], af[kc][m], acc[m][n], 0, 0, 0);
;     __builtin_amdgcn_s_setprio(0);
;     asm volatile("s_waitcnt vmcnt(0) lgkmcnt(0)" ::: "memory"); __builtin_amdgcn_s_barrier(); asm volatile("" ::: "memory");
;   }
.LBB0_95:
	s_barrier
	s_setprio 3
	s_mov_b32 m0, s37
	s_add_i32 vcc_lo, s37, 0x4000
	global_load_lds_dwordx4 v150, s[46:47]
	s_mov_b32 m0, vcc_lo
	s_add_i32 vcc_lo, s37, 0x1000
	global_load_lds_dwordx4 v151, s[46:47]
	s_mov_b32 m0, vcc_lo
	s_add_i32 vcc_lo, s37, 0x5000
	global_load_lds_dwordx4 v152, s[46:47]
	s_mov_b32 m0, vcc_lo
	s_add_i32 vcc_lo, s37, 0x2000
	global_load_lds_dwordx4 v153, s[46:47]
	s_mov_b32 m0, vcc_lo
	s_add_i32 vcc_lo, s37, 0x6000
	global_load_lds_dwordx4 v154, s[46:47]
	s_mov_b32 m0, vcc_lo
	s_add_i32 vcc_lo, s37, 0x3000
	global_load_lds_dwordx4 v155, s[46:47]
	s_mov_b32 m0, vcc_lo
	s_add_i32 vcc_lo, s37, 0x7000
	global_load_lds_dwordx4 v156, s[46:47]
	s_mov_b32 m0, vcc_lo
	s_nop 0
	global_load_lds_dwordx4 v157, s[46:47]
	v_add_u32_e32 v150, 0x80, v150
	v_add_u32_e32 v151, 0x80, v151
	v_add_u32_e32 v152, 0x80, v152
	v_add_u32_e32 v153, 0x80, v153
	v_add_u32_e32 v154, 0x80, v154
	v_add_u32_e32 v155, 0x80, v155
	v_add_u32_e32 v156, 0x80, v156
	v_add_u32_e32 v157, 0x80, v157
	v_add_u32_e32 v98, s29, v85
	v_add_u32_e32 v114, s29, v84
	v_add_u32_e32 v130, s29, v83
	v_add_u32_e32 v146, s29, v2
	ds_read_b128 v[86:89], v98
	ds_read_b128 v[90:93], v98 offset:2048
	ds_read_b128 v[94:97], v98 offset:4096
	ds_read_b128 v[98:101], v98 offset:6144
	ds_read_b128 v[102:105], v114 offset:16384
	ds_read_b128 v[106:109], v114 offset:18432
	ds_read_b128 v[110:113], v114 offset:20480
	ds_read_b128 v[114:117], v114 offset:22528
	ds_read_b128 v[118:121], v130
	ds_read_b128 v[122:125], v130 offset:2048
	ds_read_b128 v[126:129], v130 offset:4096
	ds_read_b128 v[130:133], v130 offset:6144
	ds_read_b128 v[134:137], v146 offset:16384
	ds_read_b128 v[138:141], v146 offset:18432
	ds_read_b128 v[142:145], v146 offset:20480
	ds_read_b128 v[146:149], v146 offset:22528
	s_setprio 1
	s_waitcnt lgkmcnt(0)
	v_mfma_f32_16x16x32_bf16 v[64:67], v[102:105], v[86:89], v[64:67]
	v_mfma_f32_16x16x32_bf16 v[60:63], v[106:109], v[86:89], v[60:63]
	v_mfma_f32_16x16x32_bf16 v[56:59], v[110:113], v[86:89], v[56:59]
	v_mfma_f32_16x16x32_bf16 v[52:55], v[114:117], v[86:89], v[52:55]
	v_mfma_f32_16x16x32_bf16 v[48:51], v[102:105], v[90:93], v[48:51]
	v_mfma_f32_16x16x32_bf16 v[44:47], v[106:109], v[90:93], v[44:47]
	v_mfma_f32_16x16x32_bf16 v[40:43], v[110:113], v[90:93], v[40:43]
	v_mfma_f32_16x16x32_bf16 v[36:39], v[114:117], v[90:93], v[36:39]
	v_mfma_f32_16x16x32_bf16 v[32:35], v[102:105], v[94:97], v[32:35]
	v_mfma_f32_16x16x32_bf16 v[28:31], v[106:109], v[94:97], v[28:31]
	v_mfma_f32_16x16x32_bf16 v[24:27], v[110:113], v[94:97], v[24:27]
	v_mfma_f32_16x16x32_bf16 v[20:23], v[114:117], v[94:97], v[20:23]
	v_mfma_f32_16x16x32_bf16 v[16:19], v[102:105], v[98:101], v[16:19]
	v_mfma_f32_16x16x32_bf16 v[12:15], v[106:109], v[98:101], v[12:15]
	v_mfma_f32_16x16x32_bf16 v[8:11], v[110:113], v[98:101], v[8:11]
	v_mfma_f32_16x16x32_bf16 v[4:7], v[114:117], v[98:101], v[4:7]
	v_mfma_f32_16x16x32_bf16 v[64:67], v[134:137], v[118:121], v[64:67]
	v_mfma_f32_16x16x32_bf16 v[60:63], v[138:141], v[118:121], v[60:63]
	v_mfma_f32_16x16x32_bf16 v[56:59], v[142:145], v[118:121], v[56:59]
	v_mfma_f32_16x16x32_bf16 v[52:55], v[146:149], v[118:121], v[52:55]
	v_mfma_f32_16x16x32_bf16 v[48:51], v[134:137], v[122:125], v[48:51]
	v_mfma_f32_16x16x32_bf16 v[44:47], v[138:141], v[122:125], v[44:47]
	v_mfma_f32_16x16x32_bf16 v[40:43], v[142:145], v[122:125], v[40:43]
	v_mfma_f32_16x16x32_bf16 v[36:39], v[146:149], v[122:125], v[36:39]
	v_mfma_f32_16x16x32_bf16 v[32:35], v[134:137], v[126:129], v[32:35]
	v_mfma_f32_16x16x32_bf16 v[28:31], v[138:141], v[126:129], v[28:31]
	v_mfma_f32_16x16x32_bf16 v[24:27], v[142:145], v[126:129], v[24:27]
	v_mfma_f32_16x16x32_bf16 v[20:23], v[146:149], v[126:129], v[20:23]
	v_mfma_f32_16x16x32_bf16 v[16:19], v[134:137], v[130:133], v[16:19]
	v_mfma_f32_16x16x32_bf16 v[12:15], v[138:141], v[130:133], v[12:15]
	v_mfma_f32_16x16x32_bf16 v[8:11], v[142:145], v[130:133], v[8:11]
	v_mfma_f32_16x16x32_bf16 v[4:7], v[146:149], v[130:133], v[4:7]
	s_setprio 0
	s_waitcnt vmcnt(0) lgkmcnt(0)
	s_add_u32 s24, s24, 0x80
	s_addc_u32 s25, s25, 0
	s_add_i32 s26, s26, 0x8000
	s_and_b32 s29, s26, 0x8000
	s_xor_b32 s37, s29, 0x8000
	s_add_i32 s37, s37, vcc_hi
	s_cmpk_eq_i32 s24, 0x1580
	s_cbranch_scc0 .LBB0_95
	s_barrier
; __device__ __forceinline__ void gemm_mainloop_d(const bf16_t* __restrict__ Ap, int lda, const bf16_t* __restrict__ Bt, int K,
;                                                 int m0, int n0, f32x4 (&acc)[4][4], char* lds) {
;     ...
;     const char* la = lds + st * 32768; const char* lb = la + 16384;
;     bf16x8 af[2][4], bfv[2][4];
; #pragma unroll
;     for (int kc = 0; kc < 2; kc++) {
; #pragma unroll
;       for (int m = 0; m < 4; m++) { const int row = wr * 64 + m * 16 + fr; af[kc][m] = *(const bf16x8*)(la + (row * 8 + ((kc * 4 + fq) ^ ((row >> 1) & 7))) * 16); }
; #pragma unroll
;       for (int n = 0; n < 4; n++) { const int row = wc * 64 + n * 16 + fr; bfv[kc][n] = *(const bf16x8*)(lb + (row * 8 + ((kc * 4 + fq) ^ ((row >> 1) & 7))) * 16); }
;     }
;     __builtin_amdgcn_s_setprio(1);
; #pragma unroll
;     for (int kc = 0; kc < 2; kc++)
; #pragma unroll
;       for (int m = 0; m < 4; m++)
; #pragma unroll
;         for (int n = 0; n < 4; n++) acc[m][n] = __builtin_amdgcn_mfma_f32_16x16x32_bf16(bfv[kc][n], af[kc][m], acc[m][n], 0, 0, 0);
;     __builtin_amdgcn_s_setprio(0);
;     asm volatile("s_waitcnt vmcnt(0) lgkmcnt(0)" ::: "memory"); __builtin_amdgcn_s_barrier(); asm volatile("" ::: "memory");
	v_add_u32_e32 v0, 0, v85
	ds_read_b128 v[68:71], v0 offset:32768
	ds_read_b128 v[72:75], v0 offset:34816
	ds_read_b128 v[76:79], v0 offset:36864
	ds_read_b128 v[86:89], v0 offset:38912
	v_add_u32_e32 v0, 0, v84
	ds_read_b128 v[90:93], v0 offset:49152
	ds_read_b128 v[94:97], v0 offset:51200
	ds_read_b128 v[98:101], v0 offset:53248
	ds_read_b128 v[102:105], v0 offset:55296
	v_add_u32_e32 v0, 0, v83
	s_add_u32 s24, s46, s27
	ds_read_b128 v[80:83], v0 offset:32768
	ds_read_b128 v[106:109], v0 offset:34816
	ds_read_b128 v[110:113], v0 offset:36864
	ds_read_b128 v[114:117], v0 offset:38912
	v_add_u32_e32 v0, 0, v2
	s_addc_u32 s25, s47, 0
	ds_read_b128 v[118:121], v0 offset:49152
	ds_read_b128 v[122:125], v0 offset:51200
	ds_read_b128 v[126:129], v0 offset:53248
	ds_read_b128 v[130:133], v0 offset:55296
	s_add_u32 s28, s46, s28
	s_addc_u32 s29, s47, 0
	s_add_u32 s26, s24, 0x65a8000
	s_addc_u32 s27, s25, 0
	s_add_u32 s24, s28, 0xff8c000
	s_addc_u32 s25, s29, 0
	s_setprio 1
	s_waitcnt lgkmcnt(0)
	v_mfma_f32_16x16x32_bf16 v[56:59], v[98:101], v[68:71], v[56:59]
	v_mfma_f32_16x16x32_bf16 v[48:51], v[90:93], v[72:75], v[48:51]
	v_mfma_f32_16x16x32_bf16 v[44:47], v[94:97], v[72:75], v[44:47]
	v_mfma_f32_16x16x32_bf16 v[40:43], v[98:101], v[72:75], v[40:43]
	v_mfma_f32_16x16x32_bf16 v[36:39], v[102:105], v[72:75], v[36:39]
	v_mfma_f32_16x16x32_bf16 v[32:35], v[90:93], v[76:79], v[32:35]
	v_mfma_f32_16x16x32_bf16 v[28:31], v[94:97], v[76:79], v[28:31]
	v_mfma_f32_16x16x32_bf16 v[24:27], v[98:101], v[76:79], v[24:27]
	v_mfma_f32_16x16x32_bf16 v[20:23], v[102:105], v[76:79], v[20:23]
	v_mfma_f32_16x16x32_bf16 v[16:19], v[90:93], v[86:89], v[16:19]
	v_mfma_f32_16x16x32_bf16 v[12:15], v[94:97], v[86:89], v[12:15]
	v_mfma_f32_16x16x32_bf16 v[8:11], v[98:101], v[86:89], v[8:11]
	v_mfma_f32_16x16x32_bf16 v[4:7], v[102:105], v[86:89], v[4:7]
	v_mfma_f32_16x16x32_bf16 v[64:67], v[90:93], v[68:71], v[64:67]
	v_mfma_f32_16x16x32_bf16 v[60:63], v[94:97], v[68:71], v[60:63]
	v_mfma_f32_16x16x32_bf16 v[52:55], v[102:105], v[68:71], v[52:55]
	v_mfma_f32_16x16x32_bf16 v[56:59], v[126:129], v[80:83], v[56:59]
	v_mfma_f32_16x16x32_bf16 v[48:51], v[118:121], v[106:109], v[48:51]
	v_mfma_f32_16x16x32_bf16 v[44:47], v[122:125], v[106:109], v[44:47]
	v_mfma_f32_16x16x32_bf16 v[40:43], v[126:129], v[106:109], v[40:43]
	v_mfma_f32_16x16x32_bf16 v[36:39], v[130:133], v[106:109], v[36:39]
	v_mfma_f32_16x16x32_bf16 v[32:35], v[118:121], v[110:113], v[32:35]
	v_mfma_f32_16x16x32_bf16 v[28:31], v[122:125], v[110:113], v[28:31]
	v_mfma_f32_16x16x32_bf16 v[24:27], v[126:129], v[110:113], v[24:27]
	v_mfma_f32_16x16x32_bf16 v[20:23], v[130:133], v[110:113], v[20:23]
	v_mfma_f32_16x16x32_bf16 v[16:19], v[118:121], v[114:117], v[16:19]
	v_mfma_f32_16x16x32_bf16 v[12:15], v[122:125], v[114:117], v[12:15]
	v_mfma_f32_16x16x32_bf16 v[8:11], v[126:129], v[114:117], v[8:11]
	v_mfma_f32_16x16x32_bf16 v[4:7], v[130:133], v[114:117], v[4:7]
	v_mfma_f32_16x16x32_bf16 v[64:67], v[118:121], v[80:83], v[64:67]
	v_mfma_f32_16x16x32_bf16 v[60:63], v[122:125], v[80:83], v[60:63]
	v_mfma_f32_16x16x32_bf16 v[68:71], v[130:133], v[80:83], v[52:55]
	s_setprio 0
	v_mov_b32_e32 v0, v198
	s_waitcnt vmcnt(0) lgkmcnt(0)
; __device__ __forceinline__ unsigned pk2(float lo, float hi) { unsigned r; asm("v_cvt_pk_bf16_f32 %0, %1, %2" : "=v"(r) : "v"(lo), "v"(hi)); return r; }
; __device__ __forceinline__ float bflo(unsigned u) { return __uint_as_float(u << 16); }
; __device__ __forceinline__ float bfhi(unsigned u) { return __uint_as_float(u & 0xffff0000u); }
; __device__ __forceinline__ void gemm_RES(const bf16_t* A, int K, const bf16_t* Bt, const float* xin, float* xout, bf16_t* xb, float* rss, int item, char* lds) {
;     ...
; #pragma unroll
;   for (int m = 0; m < 4; m++) {
;     const int rowg = m0 + wr * 64 + m * 16 + fr;
;     const size_t ro = (size_t)rowg * DM;
;     float sq = 0.f;
; #pragma unroll
;     for (int n = 0; n < 4; n++) {
;       const int col = n0 + wc * 64 + n * 16 + fq * 4;
;       f32x4 xv = *(const f32x4*)(xin + ro + col);
;       const f32x4 xn = xv + acc[m][n];
;       *(f32x4*)(xout + ro + col) = xn;
;       u32x2 w; w[0] = pk2(xn[0], xn[1]); w[1] = pk2(xn[2], xn[3]); *(u32x2*)(xb + ro + col) = w;
;       const float b0 = bflo(w[0]), b1 = bfhi(w[0]), b2 = bflo(w[1]), b3 = bfhi(w[1]);
;       sq += b0 * b0 + b1 * b1 + b2 * b2 + b3 * b3;
;     }
;     sq += __shfl_xor(sq, 16); sq += __shfl_xor(sq, 32);
;     if (fq == 0) unsafeAtomicAdd(rss + rowg, sq);
;   }
	v_readlane_b32 s4, v252, 35
	v_ashrrev_i32_e32 v2, 1, v0
	v_and_b32_e32 v2, 0xffffffc0, v2
	v_bfe_u32 v80, v0, 4, 2
	v_add_u32_e32 v2, s3, v2
	v_and_b32_e32 v1, 64, v0
	v_and_or_b32 v0, v0, 15, v2
	v_lshlrev_b32_e32 v2, 2, v80
	v_or3_b32 v54, v2, v1, s2
	v_ashrrev_i32_e32 v1, 31, v0
	v_lshlrev_b64 v[52:53], 12, v[0:1]
	v_readlane_b32 s18, v252, 49
	v_readlane_b32 s19, v252, 50
	v_lshlrev_b32_e32 v2, 2, v54
	v_readlane_b32 s5, v252, 36
	v_lshl_add_u64 v[52:53], s[18:19], 0, v[52:53]
	v_lshl_add_u64 v[76:77], v[52:53], 0, v[2:3]
	global_load_dwordx4 v[72:75], v[76:77], off
	v_lshlrev_b32_e32 v52, 1, v54
	v_lshlrev_b64 v[54:55], 11, v[0:1]
	v_mov_b32_e32 v53, v3
	v_lshl_add_u64 v[54:55], s[26:27], 0, v[54:55]
	v_lshl_add_u64 v[78:79], v[54:55], 0, v[52:53]
	v_readlane_b32 s6, v252, 37
	v_readlane_b32 s7, v252, 38
	v_readlane_b32 s8, v252, 39
	v_readlane_b32 s9, v252, 40
	v_readlane_b32 s10, v252, 41
	v_readlane_b32 s11, v252, 42
	v_readlane_b32 s12, v252, 43
	v_readlane_b32 s13, v252, 44
	v_readlane_b32 s14, v252, 45
	v_readlane_b32 s15, v252, 46
	v_readlane_b32 s16, v252, 47
	v_readlane_b32 s17, v252, 48
	s_waitcnt vmcnt(0)
	v_pk_add_f32 v[66:67], v[66:67], v[74:75]
	v_pk_add_f32 v[64:65], v[64:65], v[72:73]
	global_store_dwordx4 v[76:77], v[64:67], off
	v_cvt_pk_bf16_f32 v54, v64, v65
	v_cvt_pk_bf16_f32 v55, v66, v67
	global_store_dwordx2 v[78:79], v[54:55], off
	global_load_dwordx4 v[64:67], v[76:77], off offset:64
	s_waitcnt vmcnt(0)
	v_pk_add_f32 v[62:63], v[62:63], v[66:67]
	v_pk_add_f32 v[60:61], v[60:61], v[64:65]
	global_store_dwordx4 v[76:77], v[60:63], off offset:64
	v_cvt_pk_bf16_f32 v64, v60, v61
	v_cvt_pk_bf16_f32 v65, v62, v63
	global_store_dwordx2 v[78:79], v[64:65], off offset:32
	global_load_dwordx4 v[60:63], v[76:77], off offset:128
	v_lshlrev_b32_e32 v66, 16, v54
	v_and_b32_e32 v54, 0xffff0000, v54
	v_mul_f32_e32 v54, v54, v54
	v_lshlrev_b32_e32 v67, 16, v55
	v_fmac_f32_e32 v54, v66, v66
	v_and_b32_e32 v55, 0xffff0000, v55
	v_fmac_f32_e32 v54, v67, v67
	v_fmac_f32_e32 v54, v55, v55
	v_lshlrev_b32_e32 v55, 16, v64
	v_and_b32_e32 v64, 0xffff0000, v64
	v_mul_f32_e32 v64, v64, v64
	v_lshlrev_b32_e32 v66, 16, v65
	v_fmac_f32_e32 v64, v55, v55
	v_and_b32_e32 v65, 0xffff0000, v65
	v_fmac_f32_e32 v64, v66, v66
	v_fmac_f32_e32 v64, v65, v65
	v_add_f32_e32 v54, v54, v64
	s_waitcnt vmcnt(0)
	v_pk_add_f32 v[58:59], v[58:59], v[62:63]
	v_pk_add_f32 v[56:57], v[56:57], v[60:61]
	global_store_dwordx4 v[76:77], v[56:59], off offset:128
	v_cvt_pk_bf16_f32 v62, v56, v57
	v_cvt_pk_bf16_f32 v63, v58, v59
	global_store_dwordx2 v[78:79], v[62:63], off offset:64
	global_load_dwordx4 v[58:61], v[76:77], off offset:192
	v_lshlrev_b32_e32 v55, 16, v62
	v_and_b32_e32 v62, 0xffff0000, v62
	v_mul_f32_e32 v62, v62, v62
	v_lshlrev_b32_e32 v64, 16, v63
	v_fmac_f32_e32 v62, v55, v55
	v_and_b32_e32 v63, 0xffff0000, v63
	v_fmac_f32_e32 v62, v64, v64
	v_fmac_f32_e32 v62, v63, v63
	v_add_f32_e32 v54, v54, v62
	v_and_b32_e32 v57, 64, v218
	v_xor_b32_e32 v56, 16, v218
	v_add_u32_e32 v57, 64, v57
	v_cmp_lt_i32_e32 vcc, v56, v57
	s_waitcnt vmcnt(0)
	v_pk_add_f32 v[58:59], v[68:69], v[58:59]
	s_nop 0
	v_cvt_pk_bf16_f32 v62, v58, v59
	v_pk_add_f32 v[60:61], v[70:71], v[60:61]
	v_and_b32_e32 v64, 0xffff0000, v62
	v_lshlrev_b32_e32 v55, 16, v62
	v_mul_f32_e32 v64, v64, v64
	v_cvt_pk_bf16_f32 v63, v60, v61
	v_fmac_f32_e32 v64, v55, v55
	v_lshlrev_b32_e32 v65, 16, v63
	v_and_b32_e32 v66, 0xffff0000, v63
	v_fmac_f32_e32 v64, v65, v65
	v_cndmask_b32_e32 v56, v218, v56, vcc
	v_fmac_f32_e32 v64, v66, v66
	v_lshlrev_b32_e32 v56, 2, v56
	v_add_f32_e32 v54, v54, v64
	ds_bpermute_b32 v55, v56, v54
	v_xor_b32_e32 v64, 32, v218
	v_cmp_lt_i32_e32 vcc, v64, v57
	global_store_dwordx4 v[76:77], v[58:61], off offset:192
	global_store_dwordx2 v[78:79], v[62:63], off offset:96
	v_cndmask_b32_e32 v57, v218, v64, vcc
	s_waitcnt lgkmcnt(0)
	v_add_f32_e32 v54, v54, v55
	v_lshlrev_b32_e32 v57, 2, v57
	ds_bpermute_b32 v55, v57, v54
	v_cmp_eq_u32_e32 vcc, 0, v80
	s_and_saveexec_b64 s[28:29], vcc
	s_cbranch_execz .LBB0_98
	v_lshl_add_u64 v[58:59], v[0:1], 2, s[24:25]
	s_waitcnt lgkmcnt(0)
	v_add_f32_e32 v1, v54, v55
	global_atomic_add_f32 v[58:59], v1, off

; __device__ __forceinline__ void gemm_mainloop_d(const bf16_t* __restrict__ Ap, int lda, const bf16_t* __restrict__ Bt, int K,
;                                                 int m0, int n0, f32x4 (&acc)[4][4], char* lds) {
;     ...
;   for (int kt = 0; kt < nk; kt++) {
;     const int st = kt & 1;
;     if (kt + 1 < nk) dma(kt + 1, st ^ 1);
;     const char* la = lds + st * 32768; const char* lb = la + 16384;
;     bf16x8 af[2][4], bfv[2][4];
; #pragma unroll
;     for (int kc = 0; kc < 2; kc++) {
; #pragma unroll
;       for (int m = 0; m < 4; m++) { const int row = wr * 64 + m * 16 + fr; af[kc][m] = *(const bf16x8*)(la + (row * 8 + ((kc * 4 + fq) ^ ((row >> 1) & 7))) * 16); }
; #pragma unroll
;       for (int n = 0; n < 4; n++) { const int row = wc * 64 + n * 16 + fr; bfv[kc][n] = *(const bf16x8*)(lb + (row * 8 + ((kc * 4 + fq) ^ ((row >> 1) & 7))) * 16); }
;     }
;     __builtin_amdgcn_s_setprio(1);
; #pragma unroll
;     for (int kc = 0; kc < 2; kc++)
; #pragma unroll
;       for (int m = 0; m < 4; m++)
; #pragma unroll
;         for (int n = 0; n < 4; n++) acc[m][n] = __builtin_amdgcn_mfma_f32_16x16x32_bf16(bfv[kc][n], af[kc][m], acc[m][n], 0, 0, 0);
;     __builtin_amdgcn_s_setprio(0);
;     asm volatile("s_waitcnt vmcnt(0) lgkmcnt(0)" ::: "memory"); __builtin_amdgcn_s_barrier(); asm volatile("" ::: "memory");
;   }
.LBB0_109:
	s_barrier
	s_setprio 3
	s_mov_b32 m0, s35
	s_add_i32 vcc_lo, s35, 0x4000
	global_load_lds_dwordx4 v150, s[46:47]
	s_mov_b32 m0, vcc_lo
	s_add_i32 vcc_lo, s35, 0x1000
	global_load_lds_dwordx4 v151, s[46:47]
	s_mov_b32 m0, vcc_lo
	s_add_i32 vcc_lo, s35, 0x5000
	global_load_lds_dwordx4 v152, s[46:47]
	s_mov_b32 m0, vcc_lo
	s_add_i32 vcc_lo, s35, 0x2000
	global_load_lds_dwordx4 v153, s[46:47]
	s_mov_b32 m0, vcc_lo
	s_add_i32 vcc_lo, s35, 0x6000
	global_load_lds_dwordx4 v154, s[46:47]
	s_mov_b32 m0, vcc_lo
	s_add_i32 vcc_lo, s35, 0x3000
	global_load_lds_dwordx4 v155, s[46:47]
	s_mov_b32 m0, vcc_lo
	s_add_i32 vcc_lo, s35, 0x7000
	global_load_lds_dwordx4 v156, s[46:47]
	s_mov_b32 m0, vcc_lo
	s_nop 0
	global_load_lds_dwordx4 v157, s[46:47]
	v_add_u32_e32 v150, 0x80, v150
	v_add_u32_e32 v151, 0x80, v151
	v_add_u32_e32 v152, 0x80, v152
	v_add_u32_e32 v153, 0x80, v153
	v_add_u32_e32 v154, 0x80, v154
	v_add_u32_e32 v155, 0x80, v155
	v_add_u32_e32 v156, 0x80, v156
	v_add_u32_e32 v157, 0x80, v157
	v_add_u32_e32 v98, s34, v85
	v_add_u32_e32 v114, s34, v84
	v_add_u32_e32 v130, s34, v83
	v_add_u32_e32 v146, s34, v2
	ds_read_b128 v[86:89], v98
	ds_read_b128 v[90:93], v98 offset:2048
	ds_read_b128 v[94:97], v98 offset:4096
	ds_read_b128 v[98:101], v98 offset:6144
	ds_read_b128 v[102:105], v114 offset:16384
	ds_read_b128 v[106:109], v114 offset:18432
	ds_read_b128 v[110:113], v114 offset:20480
	ds_read_b128 v[114:117], v114 offset:22528
	ds_read_b128 v[118:121], v130
	ds_read_b128 v[122:125], v130 offset:2048
	ds_read_b128 v[126:129], v130 offset:4096
	ds_read_b128 v[130:133], v130 offset:6144
	ds_read_b128 v[134:137], v146 offset:16384
	ds_read_b128 v[138:141], v146 offset:18432
	ds_read_b128 v[142:145], v146 offset:20480
	ds_read_b128 v[146:149], v146 offset:22528
	s_setprio 1
	s_waitcnt lgkmcnt(0)
	v_mfma_f32_16x16x32_bf16 v[64:67], v[102:105], v[86:89], v[64:67]
	v_mfma_f32_16x16x32_bf16 v[60:63], v[106:109], v[86:89], v[60:63]
	v_mfma_f32_16x16x32_bf16 v[56:59], v[110:113], v[86:89], v[56:59]
	v_mfma_f32_16x16x32_bf16 v[52:55], v[114:117], v[86:89], v[52:55]
	v_mfma_f32_16x16x32_bf16 v[48:51], v[102:105], v[90:93], v[48:51]
	v_mfma_f32_16x16x32_bf16 v[44:47], v[106:109], v[90:93], v[44:47]
	v_mfma_f32_16x16x32_bf16 v[40:43], v[110:113], v[90:93], v[40:43]
	v_mfma_f32_16x16x32_bf16 v[36:39], v[114:117], v[90:93], v[36:39]
	v_mfma_f32_16x16x32_bf16 v[32:35], v[102:105], v[94:97], v[32:35]
	v_mfma_f32_16x16x32_bf16 v[28:31], v[106:109], v[94:97], v[28:31]
	v_mfma_f32_16x16x32_bf16 v[24:27], v[110:113], v[94:97], v[24:27]
	v_mfma_f32_16x16x32_bf16 v[20:23], v[114:117], v[94:97], v[20:23]
	v_mfma_f32_16x16x32_bf16 v[16:19], v[102:105], v[98:101], v[16:19]
	v_mfma_f32_16x16x32_bf16 v[12:15], v[106:109], v[98:101], v[12:15]
	v_mfma_f32_16x16x32_bf16 v[8:11], v[110:113], v[98:101], v[8:11]
	v_mfma_f32_16x16x32_bf16 v[4:7], v[114:117], v[98:101], v[4:7]
	v_mfma_f32_16x16x32_bf16 v[64:67], v[134:137], v[118:121], v[64:67]
	v_mfma_f32_16x16x32_bf16 v[60:63], v[138:141], v[118:121], v[60:63]
	v_mfma_f32_16x16x32_bf16 v[56:59], v[142:145], v[118:121], v[56:59]
	v_mfma_f32_16x16x32_bf16 v[52:55], v[146:149], v[118:121], v[52:55]
	v_mfma_f32_16x16x32_bf16 v[48:51], v[134:137], v[122:125], v[48:51]
	v_mfma_f32_16x16x32_bf16 v[44:47], v[138:141], v[122:125], v[44:47]
	v_mfma_f32_16x16x32_bf16 v[40:43], v[142:145], v[122:125], v[40:43]
	v_mfma_f32_16x16x32_bf16 v[36:39], v[146:149], v[122:125], v[36:39]
	v_mfma_f32_16x16x32_bf16 v[32:35], v[134:137], v[126:129], v[32:35]
	v_mfma_f32_16x16x32_bf16 v[28:31], v[138:141], v[126:129], v[28:31]
	v_mfma_f32_16x16x32_bf16 v[24:27], v[142:145], v[126:129], v[24:27]
	v_mfma_f32_16x16x32_bf16 v[20:23], v[146:149], v[126:129], v[20:23]
	v_mfma_f32_16x16x32_bf16 v[16:19], v[134:137], v[130:133], v[16:19]
	v_mfma_f32_16x16x32_bf16 v[12:15], v[138:141], v[130:133], v[12:15]
	v_mfma_f32_16x16x32_bf16 v[8:11], v[142:145], v[130:133], v[8:11]
	v_mfma_f32_16x16x32_bf16 v[4:7], v[146:149], v[130:133], v[4:7]
	s_setprio 0
	s_waitcnt vmcnt(0) lgkmcnt(0)
	s_add_u32 s26, s26, 0x80
	s_addc_u32 s27, s27, 0
	s_add_i32 s25, s25, 0x8000
	s_and_b32 s34, s25, 0x8000
	s_xor_b32 s35, s34, 0x8000
	s_add_i32 s35, s35, vcc_hi
	s_cmpk_lg_i32 s26, 0x780
	s_cbranch_scc1 .LBB0_109
	s_barrier
; __device__ __forceinline__ unsigned char* WS(const Params& p) { unsigned z = 0; asm volatile("" : "+s"(z)); return p.ws + z; }
; __device__ __forceinline__ void gemm_mainloop_d(const bf16_t* __restrict__ Ap, int lda, const bf16_t* __restrict__ Bt, int K,
;                                                 int m0, int n0, f32x4 (&acc)[4][4], char* lds) {
;     ...
;     const char* la = lds + st * 32768; const char* lb = la + 16384;
;     bf16x8 af[2][4], bfv[2][4];
; #pragma unroll
;     for (int kc = 0; kc < 2; kc++) {
; #pragma unroll
;       for (int m = 0; m < 4; m++) { const int row = wr * 64 + m * 16 + fr; af[kc][m] = *(const bf16x8*)(la + (row * 8 + ((kc * 4 + fq) ^ ((row >> 1) & 7))) * 16); }
; #pragma unroll
;       for (int n = 0; n < 4; n++) { const int row = wc * 64 + n * 16 + fr; bfv[kc][n] = *(const bf16x8*)(lb + (row * 8 + ((kc * 4 + fq) ^ ((row >> 1) & 7))) * 16); }
;     }
;     __builtin_amdgcn_s_setprio(1);
; #pragma unroll
;     for (int kc = 0; kc < 2; kc++)
; #pragma unroll
;       for (int m = 0; m < 4; m++)
; #pragma unroll
;         for (int n = 0; n < 4; n++) acc[m][n] = __builtin_amdgcn_mfma_f32_16x16x32_bf16(bfv[kc][n], af[kc][m], acc[m][n], 0, 0, 0);
;     __builtin_amdgcn_s_setprio(0);
;     asm volatile("s_waitcnt vmcnt(0) lgkmcnt(0)" ::: "memory"); __builtin_amdgcn_s_barrier(); asm volatile("" ::: "memory");
; __device__ __forceinline__ void gemm_GU(const Params& p, int item, char* lds) {
;     ...
;   GEMM_IDS
;   const float* rssg = (const float*)(WS(p) + OFF_RSS) + T + m0;
;   bf16_t* U = (bf16_t*)(WS(p) + OFF_U);
; #pragma unroll
;   for (int m = 0; m < 4; m++) {
;     const int rl = wr * 64 + m * 16 + fr; const float r = rsqrtf(rssg[rl] * (1.f / 1024.f) + 1e-6f);
	v_add_u32_e32 v0, 0, v85
	ds_read_b128 v[68:71], v0 offset:32768
	ds_read_b128 v[72:75], v0 offset:34816
	ds_read_b128 v[76:79], v0 offset:36864
	ds_read_b128 v[86:89], v0 offset:38912
	v_add_u32_e32 v0, 0, v84
	ds_read_b128 v[90:93], v0 offset:49152
	ds_read_b128 v[94:97], v0 offset:51200
	ds_read_b128 v[98:101], v0 offset:53248
	ds_read_b128 v[102:105], v0 offset:55296
	v_add_u32_e32 v0, 0, v83
	ds_read_b128 v[80:83], v0 offset:32768
	ds_read_b128 v[106:109], v0 offset:34816
	ds_read_b128 v[110:113], v0 offset:36864
	ds_read_b128 v[114:117], v0 offset:38912
	v_add_u32_e32 v0, 0, v2
	ds_read_b128 v[118:121], v0 offset:49152
	ds_read_b128 v[122:125], v0 offset:51200
	ds_read_b128 v[126:129], v0 offset:53248
	ds_read_b128 v[130:133], v0 offset:55296
	s_setprio 1
	s_waitcnt lgkmcnt(0)
	v_mfma_f32_16x16x32_bf16 v[64:67], v[90:93], v[68:71], v[64:67]
	v_mfma_f32_16x16x32_bf16 v[60:63], v[94:97], v[68:71], v[60:63]
	v_mfma_f32_16x16x32_bf16 v[56:59], v[98:101], v[68:71], v[56:59]
	v_mfma_f32_16x16x32_bf16 v[52:55], v[102:105], v[68:71], v[52:55]
	v_mfma_f32_16x16x32_bf16 v[48:51], v[90:93], v[72:75], v[48:51]
	v_mfma_f32_16x16x32_bf16 v[44:47], v[94:97], v[72:75], v[44:47]
	v_mfma_f32_16x16x32_bf16 v[68:71], v[98:101], v[72:75], v[40:43]
	v_mfma_f32_16x16x32_bf16 v[72:75], v[102:105], v[72:75], v[36:39]
	v_mfma_f32_16x16x32_bf16 v[32:35], v[90:93], v[76:79], v[32:35]
	v_mfma_f32_16x16x32_bf16 v[28:31], v[94:97], v[76:79], v[28:31]
	v_mfma_f32_16x16x32_bf16 v[134:137], v[98:101], v[76:79], v[24:27]
	v_mfma_f32_16x16x32_bf16 v[76:79], v[102:105], v[76:79], v[20:23]
	v_mfma_f32_16x16x32_bf16 v[16:19], v[90:93], v[86:89], v[16:19]
	v_mfma_f32_16x16x32_bf16 v[12:15], v[94:97], v[86:89], v[12:15]
	v_mfma_f32_16x16x32_bf16 v[90:93], v[98:101], v[86:89], v[8:11]
	v_mfma_f32_16x16x32_bf16 v[84:87], v[102:105], v[86:89], v[4:7]
	v_mfma_f32_16x16x32_bf16 v[64:67], v[118:121], v[80:83], v[64:67]
	v_mfma_f32_16x16x32_bf16 v[60:63], v[122:125], v[80:83], v[60:63]
	v_mfma_f32_16x16x32_bf16 v[56:59], v[126:129], v[80:83], v[56:59]
	v_mfma_f32_16x16x32_bf16 v[52:55], v[130:133], v[80:83], v[52:55]
	v_mfma_f32_16x16x32_bf16 v[40:43], v[118:121], v[106:109], v[48:51]
	v_mfma_f32_16x16x32_bf16 v[48:51], v[122:125], v[106:109], v[44:47]
	v_mfma_f32_16x16x32_bf16 v[36:39], v[126:129], v[106:109], v[68:71]
	v_mfma_f32_16x16x32_bf16 v[44:47], v[130:133], v[106:109], v[72:75]
	v_mfma_f32_16x16x32_bf16 v[24:27], v[118:121], v[110:113], v[32:35]
	v_mfma_f32_16x16x32_bf16 v[32:35], v[122:125], v[110:113], v[28:31]
	v_mfma_f32_16x16x32_bf16 v[20:23], v[126:129], v[110:113], v[134:137]
	v_mfma_f32_16x16x32_bf16 v[28:31], v[130:133], v[110:113], v[76:79]
	v_mfma_f32_16x16x32_bf16 v[8:11], v[118:121], v[114:117], v[16:19]
	v_mfma_f32_16x16x32_bf16 v[16:19], v[122:125], v[114:117], v[12:15]
	v_mfma_f32_16x16x32_bf16 v[4:7], v[126:129], v[114:117], v[90:93]
	v_mfma_f32_16x16x32_bf16 v[12:15], v[130:133], v[114:117], v[84:87]
	s_setprio 0
	v_mov_b32_e32 v2, v198
	s_mov_b32 s25, s89
	s_waitcnt vmcnt(0) lgkmcnt(0)
	s_add_u32 s34, s46, s25
	s_addc_u32 s35, s47, 0
	s_ashr_i32 s25, s24, 31
	v_and_b32_e32 v0, 15, v2
	s_lshl_b64 s[26:27], s[24:25], 2
	v_ashrrev_i32_e32 v1, 1, v2
	s_movk_i32 s4, 0xffc0
	s_add_u32 s26, s34, s26
	v_and_or_b32 v0, v1, s4, v0
	s_addc_u32 s27, s35, s27
	v_ashrrev_i32_e32 v1, 31, v0
	v_lshl_add_u64 v[68:69], v[0:1], 2, s[26:27]
	s_mov_b32 s26, 0xff9c000
	v_add_co_u32_e32 v70, vcc, s26, v68
	s_mov_b32 s25, s89
	s_nop 0
	v_addc_co_u32_e32 v71, vcc, 0, v69, vcc
	global_load_dword v74, v[70:71], off
	v_mov_b32_e32 v71, v64
	v_mov_b32_e32 v64, v61
	v_mov_b32_e32 v61, v66
	v_mov_b32_e32 v66, v63
	v_mov_b32_e32 v63, v56
	v_mov_b32_e32 v56, v53
	v_mov_b32_e32 v70, v60
	v_mov_b32_e32 v60, v62
	v_mov_b32_e32 v62, v52
	v_mov_b32_e32 v72, v54
	v_mov_b32_e32 v73, v58
	v_mov_b32_e32 v58, v55
	v_lshrrev_b32_e32 v1, 1, v2
	v_lshrrev_b32_e32 v2, 2, v2
	s_add_u32 s26, s46, s25
	v_and_b32_e32 v52, 12, v2
	v_add_u32_e32 v2, s24, v0
	s_addc_u32 s27, s47, 0
	s_mov_b64 s[24:25], 0xff9c000
	v_lshl_add_u64 v[54:55], v[68:69], 0, s[24:25]
	s_add_u32 s24, s26, 0x768000
	v_and_b32_e32 v1, 32, v1
	s_addc_u32 s25, s27, 0
	s_ashr_i32 s26, s31, 1
	v_or3_b32 v52, v1, s26, v52
	v_mov_b64_e32 v[0:1], s[24:25]
	v_mad_i64_i32 v[68:69], s[24:25], v2, s33, v[0:1]
	s_add_i32 s30, s30, s77
	s_add_i32 s29, s29, s2
	s_add_i32 s28, s28, s3
	s_cmpk_gt_i32 s30, 0x15ff
	s_waitcnt vmcnt(0)
; __device__ __forceinline__ unsigned pk2(float lo, float hi) { unsigned r; asm("v_cvt_pk_bf16_f32 %0, %1, %2" : "=v"(r) : "v"(lo), "v"(hi)); return r; }
; __device__ __forceinline__ float sigmoidf_(float x) { return __builtin_amdgcn_rcpf(1.0f + __expf(-x)); }
; __device__ __forceinline__ void gemm_GU(const Params& p, int item, char* lds) {
;     ...
; #pragma unroll
;   for (int m = 0; m < 4; m++) {
;     const int rl = wr * 64 + m * 16 + fr; const float r = rsqrtf(rssg[rl] * (1.f / 1024.f) + 1e-6f);
; #pragma unroll
;     for (int i = 0; i < 2; i++) {
;       f32x4 g = acc[m][2 * i] * r, u = acc[m][2 * i + 1] * r, o;
; #pragma unroll
;       for (int j = 0; j < 4; j++) o[j] = g[j] * sigmoidf_(g[j]) * u[j];
;       const int col = (n0 >> 1) + wc * 32 + i * 16 + fq * 4;
;       u32x2 w; w[0] = pk2(o[0], o[1]); w[1] = pk2(o[2], o[3]);
;       *(u32x2*)(U + (size_t)(m0 + rl) * DFF + col) = w;
;     }
	v_fmamk_f32 v53, v74, 0x3a800000, v200
	v_mul_f32_e32 v74, 0x4b800000, v53
	v_cmp_gt_f32_e32 vcc, s83, v53
	s_nop 1
	v_cndmask_b32_e32 v53, v53, v74, vcc
	v_rsq_f32_e32 v74, v53
	v_ashrrev_i32_e32 v53, 31, v52
	v_lshlrev_b64 v[52:53], 1, v[52:53]
	v_lshl_add_u64 v[68:69], v[68:69], 0, v[52:53]
	v_mul_f32_e32 v75, 0x45800000, v74
	v_cndmask_b32_e32 v74, v74, v75, vcc
	v_pk_mul_f32 v[60:61], v[60:61], v[74:75] op_sel_hi:[1,0]
	v_pk_mul_f32 v[70:71], v[70:71], v[74:75] op_sel_hi:[1,0]
	v_pk_mul_f32 v[64:65], v[64:65], v[74:75] op_sel_hi:[1,0]
	v_pk_mul_f32 v[66:67], v[66:67], v[74:75] op_sel_hi:[1,0]
	v_mul_f32_e32 v76, 0xbfb8aa3b, v61
	v_pk_mul_f32 v[62:63], v[62:63], v[74:75] op_sel_hi:[1,0]
	v_pk_mul_f32 v[56:57], v[56:57], v[74:75] op_sel_hi:[1,0]
	v_pk_mul_f32 v[72:73], v[72:73], v[74:75] op_sel_hi:[1,0]
	v_pk_mul_f32 v[58:59], v[58:59], v[74:75] op_sel_hi:[1,0]
	v_mul_f32_e32 v74, 0xbfb8aa3b, v71
	v_mul_f32_e32 v75, 0xbfb8aa3b, v65
	v_mul_f32_e32 v77, 0xbfb8aa3b, v67
	v_exp_f32_e32 v76, v76
	v_exp_f32_e32 v74, v74
	v_exp_f32_e32 v75, v75
	v_exp_f32_e32 v77, v77
	v_add_f32_e32 v76, 1.0, v76
	v_mul_f32_e32 v79, 0xbfb8aa3b, v57
	v_add_f32_e32 v74, 1.0, v74
	v_add_f32_e32 v75, 1.0, v75
	v_add_f32_e32 v77, 1.0, v77
	v_rcp_f32_e32 v76, v76
	v_mul_f32_e32 v80, 0xbfb8aa3b, v73
	v_exp_f32_e32 v79, v79
	v_rcp_f32_e32 v74, v74
	v_rcp_f32_e32 v75, v75
	v_rcp_f32_e32 v77, v77
	v_mul_f32_e32 v78, 0xbfb8aa3b, v63
	v_mul_f32_e32 v81, 0xbfb8aa3b, v59
	v_exp_f32_e32 v80, v80
	v_exp_f32_e32 v78, v78
	v_exp_f32_e32 v81, v81
	v_mul_f32_e32 v61, v61, v76
	v_add_f32_e32 v79, 1.0, v79
	v_mul_f32_e32 v71, v71, v74
	v_mul_f32_e32 v65, v65, v75
	v_mul_f32_e32 v67, v67, v77
	v_mul_f32_e32 v61, v60, v61
	v_add_f32_e32 v80, 1.0, v80
	v_rcp_f32_e32 v79, v79
	v_mul_f32_e32 v70, v70, v71
	v_mul_f32_e32 v64, v64, v65
	v_mul_f32_e32 v65, v66, v67
	v_cvt_pk_bf16_f32 v60, v70, v64
	v_cvt_pk_bf16_f32 v61, v61, v65
	v_add_f32_e32 v78, 1.0, v78
	global_store_dwordx2 v[68:69], v[60:61], off
	v_rcp_f32_e32 v60, v80
	v_add_f32_e32 v61, 1.0, v81
	v_rcp_f32_e32 v78, v78
	v_rcp_f32_e32 v61, v61
	v_mul_f32_e32 v57, v57, v79
	v_mul_f32_e32 v56, v56, v57
	v_mul_f32_e32 v57, v73, v60
	v_mul_f32_e32 v63, v63, v78
	v_mul_f32_e32 v57, v72, v57
	v_mul_f32_e32 v59, v59, v61
	v_mul_f32_e32 v62, v62, v63
	v_mul_f32_e32 v58, v58, v59
	v_cvt_pk_bf16_f32 v56, v62, v56
	v_cvt_pk_bf16_f32 v57, v57, v58
	global_store_dwordx2 v[68:69], v[56:57], off offset:32
	global_load_dword v58, v[54:55], off offset:64
	v_mov_b32_e32 v57, v40
	v_mov_b32_e32 v40, v49
	v_mov_b32_e32 v49, v42
	v_mov_b32_e32 v42, v51
	v_mov_b32_e32 v51, v36
	v_mov_b32_e32 v36, v45
	v_mov_b32_e32 v45, v38
	v_mov_b32_e32 v38, v47
	v_mov_b32_e32 v56, v48
	v_mov_b32_e32 v48, v50
	v_mov_b32_e32 v50, v44
	v_mov_b32_e32 v44, v46
	v_add_u32_e32 v46, 16, v2
	s_waitcnt vmcnt(0)
	v_fmamk_f32 v47, v58, 0x3a800000, v200
	v_mul_f32_e32 v58, 0x4b800000, v47
	v_cmp_gt_f32_e32 vcc, s83, v47
	s_nop 1
	v_cndmask_b32_e32 v47, v47, v58, vcc
	v_rsq_f32_e32 v58, v47
	v_mad_i64_i32 v[46:47], s[24:25], v46, s33, v[0:1]
	v_lshl_add_u64 v[46:47], v[46:47], 0, v[52:53]
	v_mul_f32_e32 v59, 0x45800000, v58
	v_cndmask_b32_e32 v58, v58, v59, vcc
	v_pk_mul_f32 v[56:57], v[56:57], v[58:59] op_sel_hi:[1,0]
	v_pk_mul_f32 v[40:41], v[40:41], v[58:59] op_sel_hi:[1,0]
	v_pk_mul_f32 v[48:49], v[48:49], v[58:59] op_sel_hi:[1,0]
	v_pk_mul_f32 v[42:43], v[42:43], v[58:59] op_sel_hi:[1,0]
	v_pk_mul_f32 v[36:37], v[36:37], v[58:59] op_sel_hi:[1,0]
	v_pk_mul_f32 v[38:39], v[38:39], v[58:59] op_sel_hi:[1,0]
	v_pk_mul_f32 v[50:51], v[50:51], v[58:59] op_sel_hi:[1,0]
	v_pk_mul_f32 v[44:45], v[44:45], v[58:59] op_sel_hi:[1,0]
	v_mul_f32_e32 v58, 0xbfb8aa3b, v57
	v_mul_f32_e32 v59, 0xbfb8aa3b, v41
	v_mul_f32_e32 v60, 0xbfb8aa3b, v49
	v_mul_f32_e32 v61, 0xbfb8aa3b, v43
	v_mul_f32_e32 v63, 0xbfb8aa3b, v37
	v_mul_f32_e32 v65, 0xbfb8aa3b, v39
	v_mul_f32_e32 v62, 0xbfb8aa3b, v51
	v_mul_f32_e32 v64, 0xbfb8aa3b, v45
	v_exp_f32_e32 v58, v58
	v_exp_f32_e32 v59, v59
	v_exp_f32_e32 v60, v60
	v_exp_f32_e32 v61, v61
	v_exp_f32_e32 v63, v63
	v_exp_f32_e32 v65, v65
	v_exp_f32_e32 v62, v62
	v_exp_f32_e32 v64, v64
	v_add_f32_e32 v58, 1.0, v58
	v_add_f32_e32 v59, 1.0, v59
	v_add_f32_e32 v60, 1.0, v60
	v_add_f32_e32 v61, 1.0, v61
	v_add_f32_e32 v63, 1.0, v63
	v_add_f32_e32 v65, 1.0, v65
	v_add_f32_e32 v62, 1.0, v62
	v_add_f32_e32 v64, 1.0, v64
	v_rcp_f32_e32 v58, v58
	v_rcp_f32_e32 v59, v59
	v_rcp_f32_e32 v60, v60
	v_rcp_f32_e32 v61, v61
	v_rcp_f32_e32 v63, v63
	v_rcp_f32_e32 v65, v65
	v_rcp_f32_e32 v62, v62
	v_rcp_f32_e32 v64, v64
	v_mul_f32_e32 v57, v57, v58
	v_mul_f32_e32 v41, v41, v59
	v_mul_f32_e32 v49, v49, v60
	v_mul_f32_e32 v43, v43, v61
	v_mul_f32_e32 v37, v37, v63
	v_mul_f32_e32 v39, v39, v65
	v_mul_f32_e32 v51, v51, v62
	v_mul_f32_e32 v45, v45, v64
	v_mul_f32_e32 v56, v56, v57
	v_mul_f32_e32 v40, v40, v41
	v_mul_f32_e32 v41, v48, v49
	v_mul_f32_e32 v42, v42, v43
	v_mul_f32_e32 v48, v36, v37
	v_mul_f32_e32 v39, v38, v39
	v_cvt_pk_bf16_f32 v36, v56, v40
	v_cvt_pk_bf16_f32 v37, v41, v42
	v_mul_f32_e32 v43, v50, v51
	v_mul_f32_e32 v44, v44, v45
	v_cvt_pk_bf16_f32 v38, v43, v48
	v_cvt_pk_bf16_f32 v39, v44, v39
	global_store_dwordx2 v[46:47], v[36:37], off
	global_store_dwordx2 v[46:47], v[38:39], off offset:32
	global_load_dword v38, v[54:55], off offset:128
	v_mov_b32_e32 v37, v24
	v_mov_b32_e32 v24, v33
	v_mov_b32_e32 v33, v26
	v_mov_b32_e32 v26, v35
	v_mov_b32_e32 v35, v20
	v_mov_b32_e32 v20, v29
	v_mov_b32_e32 v29, v22
	v_mov_b32_e32 v22, v31
	v_mov_b32_e32 v36, v32
	v_mov_b32_e32 v32, v34
	v_mov_b32_e32 v34, v28
	v_mov_b32_e32 v28, v30
	v_add_u32_e32 v30, 32, v2
	v_add_u32_e32 v2, 48, v2
	s_waitcnt vmcnt(0)
; __device__ __forceinline__ unsigned pk2(float lo, float hi) { unsigned r; asm("v_cvt_pk_bf16_f32 %0, %1, %2" : "=v"(r) : "v"(lo), "v"(hi)); return r; }
; __device__ __forceinline__ float sigmoidf_(float x) { return __builtin_amdgcn_rcpf(1.0f + __expf(-x)); }
; __device__ __forceinline__ void gemm_GU(const Params& p, int item, char* lds) {
;     ...
; #pragma unroll
;   for (int m = 0; m < 4; m++) {
;     const int rl = wr * 64 + m * 16 + fr; const float r = rsqrtf(rssg[rl] * (1.f / 1024.f) + 1e-6f);
; #pragma unroll
;     for (int i = 0; i < 2; i++) {
;       f32x4 g = acc[m][2 * i] * r, u = acc[m][2 * i + 1] * r, o;
; #pragma unroll
;       for (int j = 0; j < 4; j++) o[j] = g[j] * sigmoidf_(g[j]) * u[j];
;       const int col = (n0 >> 1) + wc * 32 + i * 16 + fq * 4;
;       u32x2 w; w[0] = pk2(o[0], o[1]); w[1] = pk2(o[2], o[3]);
;       *(u32x2*)(U + (size_t)(m0 + rl) * DFF + col) = w;
;     }
;   }
;   __syncthreads();
	v_fmamk_f32 v31, v38, 0x3a800000, v200
	v_mul_f32_e32 v38, 0x4b800000, v31
	v_cmp_gt_f32_e32 vcc, s83, v31
	s_nop 1
	v_cndmask_b32_e32 v31, v31, v38, vcc
	v_rsq_f32_e32 v38, v31
	v_mad_i64_i32 v[30:31], s[24:25], v30, s33, v[0:1]
	v_lshl_add_u64 v[30:31], v[30:31], 0, v[52:53]
	v_mul_f32_e32 v39, 0x45800000, v38
	v_cndmask_b32_e32 v38, v38, v39, vcc
	v_pk_mul_f32 v[36:37], v[36:37], v[38:39] op_sel_hi:[1,0]
	v_pk_mul_f32 v[24:25], v[24:25], v[38:39] op_sel_hi:[1,0]
	v_pk_mul_f32 v[32:33], v[32:33], v[38:39] op_sel_hi:[1,0]
	v_pk_mul_f32 v[26:27], v[26:27], v[38:39] op_sel_hi:[1,0]
	v_pk_mul_f32 v[20:21], v[20:21], v[38:39] op_sel_hi:[1,0]
	v_pk_mul_f32 v[22:23], v[22:23], v[38:39] op_sel_hi:[1,0]
	v_pk_mul_f32 v[34:35], v[34:35], v[38:39] op_sel_hi:[1,0]
	v_pk_mul_f32 v[28:29], v[28:29], v[38:39] op_sel_hi:[1,0]
	v_mul_f32_e32 v38, 0xbfb8aa3b, v37
	v_mul_f32_e32 v39, 0xbfb8aa3b, v25
	v_mul_f32_e32 v40, 0xbfb8aa3b, v33
	v_mul_f32_e32 v41, 0xbfb8aa3b, v27
	v_mul_f32_e32 v43, 0xbfb8aa3b, v21
	v_mul_f32_e32 v45, 0xbfb8aa3b, v23
	v_mul_f32_e32 v42, 0xbfb8aa3b, v35
	v_mul_f32_e32 v44, 0xbfb8aa3b, v29
	v_exp_f32_e32 v38, v38
	v_exp_f32_e32 v39, v39
	v_exp_f32_e32 v40, v40
	v_exp_f32_e32 v41, v41
	v_exp_f32_e32 v43, v43
	v_exp_f32_e32 v45, v45
	v_exp_f32_e32 v42, v42
	v_exp_f32_e32 v44, v44
	v_add_f32_e32 v38, 1.0, v38
	v_add_f32_e32 v39, 1.0, v39
	v_add_f32_e32 v40, 1.0, v40
	v_add_f32_e32 v41, 1.0, v41
	v_add_f32_e32 v43, 1.0, v43
	v_add_f32_e32 v45, 1.0, v45
	v_add_f32_e32 v42, 1.0, v42
	v_add_f32_e32 v44, 1.0, v44
	v_rcp_f32_e32 v38, v38
	v_rcp_f32_e32 v39, v39
	v_rcp_f32_e32 v40, v40
	v_rcp_f32_e32 v41, v41
	v_rcp_f32_e32 v43, v43
	v_rcp_f32_e32 v45, v45
	v_rcp_f32_e32 v42, v42
	v_rcp_f32_e32 v44, v44
	v_mul_f32_e32 v37, v37, v38
	v_mul_f32_e32 v25, v25, v39
	v_mul_f32_e32 v33, v33, v40
	v_mul_f32_e32 v27, v27, v41
	v_mul_f32_e32 v21, v21, v43
	v_mul_f32_e32 v23, v23, v45
	v_mul_f32_e32 v35, v35, v42
	v_mul_f32_e32 v29, v29, v44
	v_mul_f32_e32 v36, v36, v37
	v_mul_f32_e32 v24, v24, v25
	v_mul_f32_e32 v25, v32, v33
	v_mul_f32_e32 v26, v26, v27
	v_mul_f32_e32 v32, v20, v21
	v_mul_f32_e32 v23, v22, v23
	v_cvt_pk_bf16_f32 v20, v36, v24
	v_cvt_pk_bf16_f32 v21, v25, v26
	v_mul_f32_e32 v27, v34, v35
	v_mul_f32_e32 v28, v28, v29
	v_cvt_pk_bf16_f32 v22, v27, v32
	v_cvt_pk_bf16_f32 v23, v28, v23
	global_store_dwordx2 v[30:31], v[20:21], off
	global_store_dwordx2 v[30:31], v[22:23], off offset:32
	global_load_dword v22, v[54:55], off offset:192
	v_mov_b32_e32 v20, v16
	v_mov_b32_e32 v16, v18
	v_mov_b32_e32 v18, v12
	v_mov_b32_e32 v12, v14
	v_mov_b32_e32 v21, v8
	v_mov_b32_e32 v8, v17
	v_mov_b32_e32 v17, v10
	v_mov_b32_e32 v10, v19
	v_mov_b32_e32 v19, v4
	v_mov_b32_e32 v4, v13
	v_mov_b32_e32 v13, v6
	v_mov_b32_e32 v6, v15
	v_mad_i64_i32 v[0:1], s[24:25], v2, s33, v[0:1]
	v_lshl_add_u64 v[0:1], v[0:1], 0, v[52:53]
	s_waitcnt vmcnt(0)
	v_fmamk_f32 v14, v22, 0x3a800000, v200
	v_mul_f32_e32 v15, 0x4b800000, v14
	v_cmp_gt_f32_e32 vcc, s83, v14
	s_nop 1
	v_cndmask_b32_e32 v14, v14, v15, vcc
	v_rsq_f32_e32 v14, v14
	s_nop 0
	v_mul_f32_e32 v2, 0x45800000, v14
	v_cndmask_b32_e32 v2, v14, v2, vcc
	v_pk_mul_f32 v[14:15], v[20:21], v[2:3] op_sel_hi:[1,0]
	v_pk_mul_f32 v[8:9], v[8:9], v[2:3] op_sel_hi:[1,0]
	v_pk_mul_f32 v[16:17], v[16:17], v[2:3] op_sel_hi:[1,0]
	v_pk_mul_f32 v[10:11], v[10:11], v[2:3] op_sel_hi:[1,0]
	v_pk_mul_f32 v[4:5], v[4:5], v[2:3] op_sel_hi:[1,0]
	v_pk_mul_f32 v[6:7], v[6:7], v[2:3] op_sel_hi:[1,0]
	v_pk_mul_f32 v[18:19], v[18:19], v[2:3] op_sel_hi:[1,0]
	v_pk_mul_f32 v[12:13], v[12:13], v[2:3] op_sel_hi:[1,0]
	v_mul_f32_e32 v2, 0xbfb8aa3b, v15
	v_mul_f32_e32 v20, 0xbfb8aa3b, v9
	v_mul_f32_e32 v21, 0xbfb8aa3b, v17
	v_mul_f32_e32 v22, 0xbfb8aa3b, v11
	v_mul_f32_e32 v24, 0xbfb8aa3b, v5
	v_mul_f32_e32 v26, 0xbfb8aa3b, v7
	v_mul_f32_e32 v23, 0xbfb8aa3b, v19
	v_mul_f32_e32 v25, 0xbfb8aa3b, v13
	v_exp_f32_e32 v2, v2
	v_exp_f32_e32 v20, v20
	v_exp_f32_e32 v21, v21
	v_exp_f32_e32 v22, v22
	v_exp_f32_e32 v24, v24
	v_exp_f32_e32 v26, v26
	v_exp_f32_e32 v23, v23
	v_exp_f32_e32 v25, v25
	v_add_f32_e32 v2, 1.0, v2
	v_add_f32_e32 v20, 1.0, v20
	v_add_f32_e32 v21, 1.0, v21
	v_add_f32_e32 v22, 1.0, v22
	v_add_f32_e32 v24, 1.0, v24
	v_add_f32_e32 v26, 1.0, v26
	v_add_f32_e32 v23, 1.0, v23
	v_add_f32_e32 v25, 1.0, v25
	v_rcp_f32_e32 v2, v2
	v_rcp_f32_e32 v20, v20
	v_rcp_f32_e32 v21, v21
	v_rcp_f32_e32 v22, v22
	v_rcp_f32_e32 v24, v24
	v_rcp_f32_e32 v26, v26
	v_rcp_f32_e32 v23, v23
	v_rcp_f32_e32 v25, v25
	v_mul_f32_e32 v2, v15, v2
	v_mul_f32_e32 v9, v9, v20
	v_mul_f32_e32 v15, v17, v21
	v_mul_f32_e32 v11, v11, v22
	v_mul_f32_e32 v5, v5, v24
	v_mul_f32_e32 v7, v7, v26
	v_mul_f32_e32 v17, v19, v23
	v_mul_f32_e32 v13, v13, v25
	v_mul_f32_e32 v2, v14, v2
	v_mul_f32_e32 v8, v8, v9
	v_mul_f32_e32 v9, v16, v15
	v_mul_f32_e32 v10, v10, v11
	v_mul_f32_e32 v14, v4, v5
	v_mul_f32_e32 v7, v6, v7
	v_cvt_pk_bf16_f32 v4, v2, v8
	v_cvt_pk_bf16_f32 v5, v9, v10
	v_mul_f32_e32 v11, v18, v17
	v_mul_f32_e32 v12, v12, v13
	v_cvt_pk_bf16_f32 v6, v11, v14
	v_cvt_pk_bf16_f32 v7, v12, v7
	global_store_dwordx2 v[0:1], v[4:5], off
	global_store_dwordx2 v[0:1], v[6:7], off offset:32
	s_cbranch_scc0 .LBB0_108

; __device__ __forceinline__ void gemm_mainloop_d(const bf16_t* __restrict__ Ap, int lda, const bf16_t* __restrict__ Bt, int K,
;                                                 int m0, int n0, f32x4 (&acc)[4][4], char* lds) {
;     ...
;   for (int kt = 0; kt < nk; kt++) {
;     const int st = kt & 1;
;     if (kt + 1 < nk) dma(kt + 1, st ^ 1);
;     const char* la = lds + st * 32768; const char* lb = la + 16384;
;     bf16x8 af[2][4], bfv[2][4];
; #pragma unroll
;     for (int kc = 0; kc < 2; kc++) {
; #pragma unroll
;       for (int m = 0; m < 4; m++) { const int row = wr * 64 + m * 16 + fr; af[kc][m] = *(const bf16x8*)(la + (row * 8 + ((kc * 4 + fq) ^ ((row >> 1) & 7))) * 16); }
; #pragma unroll
;       for (int n = 0; n < 4; n++) { const int row = wc * 64 + n * 16 + fr; bfv[kc][n] = *(const bf16x8*)(lb + (row * 8 + ((kc * 4 + fq) ^ ((row >> 1) & 7))) * 16); }
;     }
;     __builtin_amdgcn_s_setprio(1);
; #pragma unroll
;     for (int kc = 0; kc < 2; kc++)
; #pragma unroll
;       for (int m = 0; m < 4; m++)
; #pragma unroll
;         for (int n = 0; n < 4; n++) acc[m][n] = __builtin_amdgcn_mfma_f32_16x16x32_bf16(bfv[kc][n], af[kc][m], acc[m][n], 0, 0, 0);
;     __builtin_amdgcn_s_setprio(0);
;     asm volatile("s_waitcnt vmcnt(0) lgkmcnt(0)" ::: "memory"); __builtin_amdgcn_s_barrier(); asm volatile("" ::: "memory");
;   }
.LBB0_126:
	s_barrier
	s_setprio 3
	s_mov_b32 m0, s43
	s_add_i32 vcc_lo, s43, 0x4000
	global_load_lds_dwordx4 v150, s[46:47]
	s_mov_b32 m0, vcc_lo
	s_add_i32 vcc_lo, s43, 0x1000
	global_load_lds_dwordx4 v151, s[46:47]
	s_mov_b32 m0, vcc_lo
	s_add_i32 vcc_lo, s43, 0x5000
	global_load_lds_dwordx4 v152, s[46:47]
	s_mov_b32 m0, vcc_lo
	s_add_i32 vcc_lo, s43, 0x2000
	global_load_lds_dwordx4 v153, s[46:47]
	s_mov_b32 m0, vcc_lo
	s_add_i32 vcc_lo, s43, 0x6000
	global_load_lds_dwordx4 v154, s[46:47]
	s_mov_b32 m0, vcc_lo
	s_add_i32 vcc_lo, s43, 0x3000
	global_load_lds_dwordx4 v155, s[46:47]
	s_mov_b32 m0, vcc_lo
	s_add_i32 vcc_lo, s43, 0x7000
	global_load_lds_dwordx4 v156, s[46:47]
	s_mov_b32 m0, vcc_lo
	s_nop 0
	global_load_lds_dwordx4 v157, s[46:47]
	v_add_u32_e32 v150, 0x80, v150
	v_add_u32_e32 v151, 0x80, v151
	v_add_u32_e32 v152, 0x80, v152
	v_add_u32_e32 v153, 0x80, v153
	v_add_u32_e32 v154, 0x80, v154
	v_add_u32_e32 v155, 0x80, v155
	v_add_u32_e32 v156, 0x80, v156
	v_add_u32_e32 v157, 0x80, v157
	v_add_u32_e32 v98, s37, v85
	v_add_u32_e32 v114, s37, v84
	v_add_u32_e32 v130, s37, v83
	v_add_u32_e32 v146, s37, v2
	ds_read_b128 v[86:89], v98
	ds_read_b128 v[90:93], v98 offset:2048
	ds_read_b128 v[94:97], v98 offset:4096
	ds_read_b128 v[98:101], v98 offset:6144
	ds_read_b128 v[102:105], v114 offset:16384
	ds_read_b128 v[106:109], v114 offset:18432
	ds_read_b128 v[110:113], v114 offset:20480
	ds_read_b128 v[114:117], v114 offset:22528
	ds_read_b128 v[118:121], v130
	ds_read_b128 v[122:125], v130 offset:2048
	ds_read_b128 v[126:129], v130 offset:4096
	ds_read_b128 v[130:133], v130 offset:6144
	ds_read_b128 v[134:137], v146 offset:16384
	ds_read_b128 v[138:141], v146 offset:18432
	ds_read_b128 v[142:145], v146 offset:20480
	ds_read_b128 v[146:149], v146 offset:22528
	s_setprio 1
	s_waitcnt lgkmcnt(0)
	v_mfma_f32_16x16x32_bf16 v[64:67], v[102:105], v[86:89], v[64:67]
	v_mfma_f32_16x16x32_bf16 v[60:63], v[106:109], v[86:89], v[60:63]
	v_mfma_f32_16x16x32_bf16 v[56:59], v[110:113], v[86:89], v[56:59]
	v_mfma_f32_16x16x32_bf16 v[52:55], v[114:117], v[86:89], v[52:55]
	v_mfma_f32_16x16x32_bf16 v[48:51], v[102:105], v[90:93], v[48:51]
	v_mfma_f32_16x16x32_bf16 v[44:47], v[106:109], v[90:93], v[44:47]
	v_mfma_f32_16x16x32_bf16 v[40:43], v[110:113], v[90:93], v[40:43]
	v_mfma_f32_16x16x32_bf16 v[36:39], v[114:117], v[90:93], v[36:39]
	v_mfma_f32_16x16x32_bf16 v[32:35], v[102:105], v[94:97], v[32:35]
	v_mfma_f32_16x16x32_bf16 v[28:31], v[106:109], v[94:97], v[28:31]
	v_mfma_f32_16x16x32_bf16 v[24:27], v[110:113], v[94:97], v[24:27]
	v_mfma_f32_16x16x32_bf16 v[20:23], v[114:117], v[94:97], v[20:23]
	v_mfma_f32_16x16x32_bf16 v[16:19], v[102:105], v[98:101], v[16:19]
	v_mfma_f32_16x16x32_bf16 v[12:15], v[106:109], v[98:101], v[12:15]
	v_mfma_f32_16x16x32_bf16 v[8:11], v[110:113], v[98:101], v[8:11]
	v_mfma_f32_16x16x32_bf16 v[4:7], v[114:117], v[98:101], v[4:7]
	v_mfma_f32_16x16x32_bf16 v[64:67], v[134:137], v[118:121], v[64:67]
	v_mfma_f32_16x16x32_bf16 v[60:63], v[138:141], v[118:121], v[60:63]
	v_mfma_f32_16x16x32_bf16 v[56:59], v[142:145], v[118:121], v[56:59]
	v_mfma_f32_16x16x32_bf16 v[52:55], v[146:149], v[118:121], v[52:55]
	v_mfma_f32_16x16x32_bf16 v[48:51], v[134:137], v[122:125], v[48:51]
	v_mfma_f32_16x16x32_bf16 v[44:47], v[138:141], v[122:125], v[44:47]
	v_mfma_f32_16x16x32_bf16 v[40:43], v[142:145], v[122:125], v[40:43]
	v_mfma_f32_16x16x32_bf16 v[36:39], v[146:149], v[122:125], v[36:39]
	v_mfma_f32_16x16x32_bf16 v[32:35], v[134:137], v[126:129], v[32:35]
	v_mfma_f32_16x16x32_bf16 v[28:31], v[138:141], v[126:129], v[28:31]
	v_mfma_f32_16x16x32_bf16 v[24:27], v[142:145], v[126:129], v[24:27]
	v_mfma_f32_16x16x32_bf16 v[20:23], v[146:149], v[126:129], v[20:23]
	v_mfma_f32_16x16x32_bf16 v[16:19], v[134:137], v[130:133], v[16:19]
	v_mfma_f32_16x16x32_bf16 v[12:15], v[138:141], v[130:133], v[12:15]
	v_mfma_f32_16x16x32_bf16 v[8:11], v[142:145], v[130:133], v[8:11]
	v_mfma_f32_16x16x32_bf16 v[4:7], v[146:149], v[130:133], v[4:7]
	s_setprio 0
	s_waitcnt vmcnt(0) lgkmcnt(0)
	s_add_u32 s30, s30, 0x80
	s_addc_u32 s31, s31, 0
	s_add_i32 s34, s34, 0x8000
	s_and_b32 s37, s34, 0x8000
	s_xor_b32 s43, s37, 0x8000
	s_add_i32 s43, s43, vcc_hi
	s_cmpk_eq_i32 s30, 0x780
	s_cbranch_scc0 .LBB0_126
	s_barrier
; __device__ __forceinline__ void gemm_mainloop_d(const bf16_t* __restrict__ Ap, int lda, const bf16_t* __restrict__ Bt, int K,
;                                                 int m0, int n0, f32x4 (&acc)[4][4], char* lds) {
;     ...
;     const char* la = lds + st * 32768; const char* lb = la + 16384;
;     bf16x8 af[2][4], bfv[2][4];
; #pragma unroll
;     for (int kc = 0; kc < 2; kc++) {
; #pragma unroll
;       for (int m = 0; m < 4; m++) { const int row = wr * 64 + m * 16 + fr; af[kc][m] = *(const bf16x8*)(la + (row * 8 + ((kc * 4 + fq) ^ ((row >> 1) & 7))) * 16); }
; #pragma unroll
;       for (int n = 0; n < 4; n++) { const int row = wc * 64 + n * 16 + fr; bfv[kc][n] = *(const bf16x8*)(lb + (row * 8 + ((kc * 4 + fq) ^ ((row >> 1) & 7))) * 16); }
;     }
;     __builtin_amdgcn_s_setprio(1);
; #pragma unroll
;     for (int kc = 0; kc < 2; kc++)
; #pragma unroll
;       for (int m = 0; m < 4; m++)
; #pragma unroll
;         for (int n = 0; n < 4; n++) acc[m][n] = __builtin_amdgcn_mfma_f32_16x16x32_bf16(bfv[kc][n], af[kc][m], acc[m][n], 0, 0, 0);
	v_add_u32_e32 v0, 0, v85
	ds_read_b128 v[68:71], v0 offset:32768
	ds_read_b128 v[72:75], v0 offset:34816
	ds_read_b128 v[76:79], v0 offset:36864
	ds_read_b128 v[86:89], v0 offset:38912
	v_add_u32_e32 v0, 0, v84
	ds_read_b128 v[90:93], v0 offset:49152
	ds_read_b128 v[94:97], v0 offset:51200
	ds_read_b128 v[98:101], v0 offset:53248
	ds_read_b128 v[102:105], v0 offset:55296
	v_add_u32_e32 v0, 0, v83
	s_add_u32 s30, s46, s35
	ds_read_b128 v[80:83], v0 offset:32768
	ds_read_b128 v[106:109], v0 offset:34816
	ds_read_b128 v[110:113], v0 offset:36864
	ds_read_b128 v[114:117], v0 offset:38912
	v_add_u32_e32 v0, 0, v2
	s_addc_u32 s31, s47, 0
	ds_read_b128 v[118:121], v0 offset:49152
	ds_read_b128 v[122:125], v0 offset:51200
	ds_read_b128 v[126:129], v0 offset:53248
	ds_read_b128 v[130:133], v0 offset:55296
	s_add_u32 s36, s46, s36
	s_addc_u32 s37, s47, 0
	s_add_u32 s34, s30, 0x65a8000
	s_addc_u32 s35, s31, 0
	s_add_u32 s30, s36, 0xff9c000
	s_addc_u32 s31, s37, 0
	s_setprio 1
	s_waitcnt lgkmcnt(0)
	v_mfma_f32_16x16x32_bf16 v[56:59], v[98:101], v[68:71], v[56:59]
	v_mfma_f32_16x16x32_bf16 v[48:51], v[90:93], v[72:75], v[48:51]
	v_mfma_f32_16x16x32_bf16 v[44:47], v[94:97], v[72:75], v[44:47]
	v_mfma_f32_16x16x32_bf16 v[40:43], v[98:101], v[72:75], v[40:43]
	v_mfma_f32_16x16x32_bf16 v[36:39], v[102:105], v[72:75], v[36:39]
	v_mfma_f32_16x16x32_bf16 v[32:35], v[90:93], v[76:79], v[32:35]
	v_mfma_f32_16x16x32_bf16 v[28:31], v[94:97], v[76:79], v[28:31]
	v_mfma_f32_16x16x32_bf16 v[24:27], v[98:101], v[76:79], v[24:27]
	v_mfma_f32_16x16x32_bf16 v[20:23], v[102:105], v[76:79], v[20:23]
	v_mfma_f32_16x16x32_bf16 v[16:19], v[90:93], v[86:89], v[16:19]
	v_mfma_f32_16x16x32_bf16 v[12:15], v[94:97], v[86:89], v[12:15]
	v_mfma_f32_16x16x32_bf16 v[8:11], v[98:101], v[86:89], v[8:11]
	v_mfma_f32_16x16x32_bf16 v[4:7], v[102:105], v[86:89], v[4:7]
	v_mfma_f32_16x16x32_bf16 v[64:67], v[90:93], v[68:71], v[64:67]
	v_mfma_f32_16x16x32_bf16 v[60:63], v[94:97], v[68:71], v[60:63]
	v_mfma_f32_16x16x32_bf16 v[52:55], v[102:105], v[68:71], v[52:55]
	v_mfma_f32_16x16x32_bf16 v[56:59], v[126:129], v[80:83], v[56:59]
	v_mfma_f32_16x16x32_bf16 v[48:51], v[118:121], v[106:109], v[48:51]
	v_mfma_f32_16x16x32_bf16 v[44:47], v[122:125], v[106:109], v[44:47]
	v_mfma_f32_16x16x32_bf16 v[40:43], v[126:129], v[106:109], v[40:43]
	v_mfma_f32_16x16x32_bf16 v[36:39], v[130:133], v[106:109], v[36:39]
	v_mfma_f32_16x16x32_bf16 v[32:35], v[118:121], v[110:113], v[32:35]
	v_mfma_f32_16x16x32_bf16 v[28:31], v[122:125], v[110:113], v[28:31]
	v_mfma_f32_16x16x32_bf16 v[24:27], v[126:129], v[110:113], v[24:27]
	v_mfma_f32_16x16x32_bf16 v[20:23], v[130:133], v[110:113], v[20:23]
	v_mfma_f32_16x16x32_bf16 v[16:19], v[118:121], v[114:117], v[16:19]
	v_mfma_f32_16x16x32_bf16 v[12:15], v[122:125], v[114:117], v[12:15]
	v_mfma_f32_16x16x32_bf16 v[8:11], v[126:129], v[114:117], v[8:11]
	v_mfma_f32_16x16x32_bf16 v[4:7], v[130:133], v[114:117], v[4:7]
	v_mfma_f32_16x16x32_bf16 v[64:67], v[118:121], v[80:83], v[64:67]
	v_mfma_f32_16x16x32_bf16 v[60:63], v[122:125], v[80:83], v[60:63]
	v_mfma_f32_16x16x32_bf16 v[68:71], v[130:133], v[80:83], v[52:55]
	s_setprio 0
	v_mov_b32_e32 v0, v198
	s_waitcnt vmcnt(0) lgkmcnt(0)
; __device__ __forceinline__ unsigned pk2(float lo, float hi) { unsigned r; asm("v_cvt_pk_bf16_f32 %0, %1, %2" : "=v"(r) : "v"(lo), "v"(hi)); return r; }
; __device__ __forceinline__ float bflo(unsigned u) { return __uint_as_float(u << 16); }
; __device__ __forceinline__ float bfhi(unsigned u) { return __uint_as_float(u & 0xffff0000u); }
; __device__ __forceinline__ void gemm_RES(const bf16_t* A, int K, const bf16_t* Bt, const float* xin, float* xout, bf16_t* xb, float* rss, int item, char* lds) {
;     ...
; #pragma unroll
;   for (int m = 0; m < 4; m++) {
;     const int rowg = m0 + wr * 64 + m * 16 + fr;
;     const size_t ro = (size_t)rowg * DM;
;     float sq = 0.f;
; #pragma unroll
;     for (int n = 0; n < 4; n++) {
;       const int col = n0 + wc * 64 + n * 16 + fq * 4;
;       f32x4 xv = *(const f32x4*)(xin + ro + col);
;       const f32x4 xn = xv + acc[m][n];
;       *(f32x4*)(xout + ro + col) = xn;
;       u32x2 w; w[0] = pk2(xn[0], xn[1]); w[1] = pk2(xn[2], xn[3]); *(u32x2*)(xb + ro + col) = w;
;       const float b0 = bflo(w[0]), b1 = bfhi(w[0]), b2 = bflo(w[1]), b3 = bfhi(w[1]);
;       sq += b0 * b0 + b1 * b1 + b2 * b2 + b3 * b3;
;     }
;     sq += __shfl_xor(sq, 16); sq += __shfl_xor(sq, 32);
;     if (fq == 0) unsafeAtomicAdd(rss + rowg, sq);
;   }
	v_readlane_b32 s4, v252, 35
	v_ashrrev_i32_e32 v2, 1, v0
	v_and_b32_e32 v2, 0xffffffc0, v2
	v_add_u32_e32 v2, s3, v2
	v_bfe_u32 v82, v0, 4, 2
	v_and_or_b32 v52, v0, 15, v2
	v_and_b32_e32 v1, 64, v0
	v_lshlrev_b32_e32 v0, 2, v82
	v_ashrrev_i32_e32 v53, 31, v52
	v_or3_b32 v78, v0, v1, s2
	v_lshlrev_b64 v[54:55], 12, v[52:53]
	v_lshl_add_u64 v[0:1], s[26:27], 0, v[54:55]
	v_lshlrev_b32_e32 v2, 2, v78
	v_lshl_add_u64 v[76:77], v[0:1], 0, v[2:3]
	global_load_dwordx4 v[72:75], v[76:77], off
	v_lshlrev_b32_e32 v0, 1, v78
	v_lshlrev_b64 v[78:79], 11, v[52:53]
	v_readlane_b32 s18, v252, 49
	v_readlane_b32 s19, v252, 50
	v_mov_b32_e32 v1, v3
	v_lshl_add_u64 v[78:79], s[34:35], 0, v[78:79]
	v_lshl_add_u64 v[54:55], s[18:19], 0, v[54:55]
	v_lshl_add_u64 v[80:81], v[54:55], 0, v[2:3]
	v_lshl_add_u64 v[78:79], v[78:79], 0, v[0:1]
	v_readlane_b32 s5, v252, 36
	v_readlane_b32 s6, v252, 37
	v_readlane_b32 s7, v252, 38
	v_readlane_b32 s8, v252, 39
	v_readlane_b32 s9, v252, 40
	v_readlane_b32 s10, v252, 41
	v_readlane_b32 s11, v252, 42
	v_readlane_b32 s12, v252, 43
	v_readlane_b32 s13, v252, 44
	v_readlane_b32 s14, v252, 45
	v_readlane_b32 s15, v252, 46
	v_readlane_b32 s16, v252, 47
	v_readlane_b32 s17, v252, 48
	s_waitcnt vmcnt(0)
	v_pk_add_f32 v[66:67], v[66:67], v[74:75]
	v_pk_add_f32 v[64:65], v[64:65], v[72:73]
	global_store_dwordx4 v[80:81], v[64:67], off
	v_cvt_pk_bf16_f32 v54, v64, v65
	v_cvt_pk_bf16_f32 v55, v66, v67
	global_store_dwordx2 v[78:79], v[54:55], off
	global_load_dwordx4 v[64:67], v[76:77], off offset:64
	s_waitcnt vmcnt(0)
	v_pk_add_f32 v[62:63], v[62:63], v[66:67]
	v_pk_add_f32 v[60:61], v[60:61], v[64:65]
	global_store_dwordx4 v[80:81], v[60:63], off offset:64
	v_cvt_pk_bf16_f32 v64, v60, v61
	v_cvt_pk_bf16_f32 v65, v62, v63
	global_store_dwordx2 v[78:79], v[64:65], off offset:32
	global_load_dwordx4 v[60:63], v[76:77], off offset:128
	v_lshlrev_b32_e32 v66, 16, v54
	v_and_b32_e32 v54, 0xffff0000, v54
	v_mul_f32_e32 v54, v54, v54
	v_lshlrev_b32_e32 v67, 16, v55
	v_fmac_f32_e32 v54, v66, v66
	v_and_b32_e32 v55, 0xffff0000, v55
	v_fmac_f32_e32 v54, v67, v67
	v_fmac_f32_e32 v54, v55, v55
	v_lshlrev_b32_e32 v55, 16, v64
	v_and_b32_e32 v64, 0xffff0000, v64
	v_mul_f32_e32 v64, v64, v64
	v_lshlrev_b32_e32 v66, 16, v65
	v_fmac_f32_e32 v64, v55, v55
	v_and_b32_e32 v65, 0xffff0000, v65
	v_fmac_f32_e32 v64, v66, v66
	v_fmac_f32_e32 v64, v65, v65
	v_add_f32_e32 v54, v54, v64
	s_waitcnt vmcnt(0)
	v_pk_add_f32 v[58:59], v[58:59], v[62:63]
	v_pk_add_f32 v[56:57], v[56:57], v[60:61]
	global_store_dwordx4 v[80:81], v[56:59], off offset:128
	v_cvt_pk_bf16_f32 v62, v56, v57
	v_cvt_pk_bf16_f32 v63, v58, v59
	global_store_dwordx2 v[78:79], v[62:63], off offset:64
	global_load_dwordx4 v[58:61], v[76:77], off offset:192
	v_lshlrev_b32_e32 v55, 16, v62
	v_and_b32_e32 v62, 0xffff0000, v62
	v_mul_f32_e32 v62, v62, v62
	v_lshlrev_b32_e32 v64, 16, v63
	v_fmac_f32_e32 v62, v55, v55
	v_and_b32_e32 v63, 0xffff0000, v63
	v_fmac_f32_e32 v62, v64, v64
	v_fmac_f32_e32 v62, v63, v63
	v_add_f32_e32 v54, v54, v62
	v_and_b32_e32 v57, 64, v218
	v_xor_b32_e32 v56, 16, v218
	v_add_u32_e32 v57, 64, v57
	v_cmp_lt_i32_e32 vcc, v56, v57
	s_waitcnt vmcnt(0)
	v_pk_add_f32 v[58:59], v[68:69], v[58:59]
	s_nop 0
	v_cvt_pk_bf16_f32 v62, v58, v59
	v_pk_add_f32 v[60:61], v[70:71], v[60:61]
	v_and_b32_e32 v64, 0xffff0000, v62
	v_lshlrev_b32_e32 v55, 16, v62
	v_mul_f32_e32 v64, v64, v64
	v_cvt_pk_bf16_f32 v63, v60, v61
	v_fmac_f32_e32 v64, v55, v55
	v_lshlrev_b32_e32 v65, 16, v63
	v_and_b32_e32 v66, 0xffff0000, v63
	v_fmac_f32_e32 v64, v65, v65
	v_cndmask_b32_e32 v56, v218, v56, vcc
	v_fmac_f32_e32 v64, v66, v66
	v_lshlrev_b32_e32 v56, 2, v56
	v_add_f32_e32 v54, v54, v64
	ds_bpermute_b32 v55, v56, v54
	v_xor_b32_e32 v64, 32, v218
	v_cmp_lt_i32_e32 vcc, v64, v57
	global_store_dwordx4 v[80:81], v[58:61], off offset:192
	global_store_dwordx2 v[78:79], v[62:63], off offset:96
	v_cndmask_b32_e32 v57, v218, v64, vcc
	s_waitcnt lgkmcnt(0)
	v_add_f32_e32 v54, v54, v55
	v_lshlrev_b32_e32 v57, 2, v57
	ds_bpermute_b32 v55, v57, v54
	v_cmp_eq_u32_e32 vcc, 0, v82
	s_and_saveexec_b64 s[36:37], vcc
	s_cbranch_execz .LBB0_129
	v_lshl_add_u64 v[58:59], v[52:53], 2, s[30:31]
	s_waitcnt lgkmcnt(0)
	v_add_f32_e32 v53, v54, v55
	global_atomic_add_f32 v[58:59], v53, off

; __device__ __forceinline__ void gemm_mainloop_d(const bf16_t* __restrict__ Ap, int lda, const bf16_t* __restrict__ Bt, int K,
;                                                 int m0, int n0, f32x4 (&acc)[4][4], char* lds) {
;     ...
;   for (int kt = 0; kt < nk; kt++) {
;     const int st = kt & 1;
;     if (kt + 1 < nk) dma(kt + 1, st ^ 1);
;     const char* la = lds + st * 32768; const char* lb = la + 16384;
;     bf16x8 af[2][4], bfv[2][4];
; #pragma unroll
;     for (int kc = 0; kc < 2; kc++) {
; #pragma unroll
;       for (int m = 0; m < 4; m++) { const int row = wr * 64 + m * 16 + fr; af[kc][m] = *(const bf16x8*)(la + (row * 8 + ((kc * 4 + fq) ^ ((row >> 1) & 7))) * 16); }
; #pragma unroll
;       for (int n = 0; n < 4; n++) { const int row = wc * 64 + n * 16 + fr; bfv[kc][n] = *(const bf16x8*)(lb + (row * 8 + ((kc * 4 + fq) ^ ((row >> 1) & 7))) * 16); }
;     }
;     __builtin_amdgcn_s_setprio(1);
; #pragma unroll
;     for (int kc = 0; kc < 2; kc++)
; #pragma unroll
;       for (int m = 0; m < 4; m++)
; #pragma unroll
;         for (int n = 0; n < 4; n++) acc[m][n] = __builtin_amdgcn_mfma_f32_16x16x32_bf16(bfv[kc][n], af[kc][m], acc[m][n], 0, 0, 0);
;     __builtin_amdgcn_s_setprio(0);
;     asm volatile("s_waitcnt vmcnt(0) lgkmcnt(0)" ::: "memory"); __builtin_amdgcn_s_barrier(); asm volatile("" ::: "memory");
;   }
.LBB0_657:
	s_barrier
	s_setprio 3
	s_mov_b32 m0, s29
	s_add_i32 vcc_lo, s29, 0x4000
	global_load_lds_dwordx4 v150, s[46:47]
	s_mov_b32 m0, vcc_lo
	s_add_i32 vcc_lo, s29, 0x1000
	global_load_lds_dwordx4 v151, s[46:47]
	s_mov_b32 m0, vcc_lo
	s_add_i32 vcc_lo, s29, 0x5000
	global_load_lds_dwordx4 v152, s[46:47]
	s_mov_b32 m0, vcc_lo
	s_add_i32 vcc_lo, s29, 0x2000
	global_load_lds_dwordx4 v153, s[46:47]
	s_mov_b32 m0, vcc_lo
	s_add_i32 vcc_lo, s29, 0x6000
	global_load_lds_dwordx4 v154, s[46:47]
	s_mov_b32 m0, vcc_lo
	s_add_i32 vcc_lo, s29, 0x3000
	global_load_lds_dwordx4 v155, s[46:47]
	s_mov_b32 m0, vcc_lo
	s_add_i32 vcc_lo, s29, 0x7000
	global_load_lds_dwordx4 v156, s[46:47]
	s_mov_b32 m0, vcc_lo
	s_nop 0
	global_load_lds_dwordx4 v157, s[46:47]
	v_add_u32_e32 v150, 0x80, v150
	v_add_u32_e32 v151, 0x80, v151
	v_add_u32_e32 v152, 0x80, v152
	v_add_u32_e32 v153, 0x80, v153
	v_add_u32_e32 v154, 0x80, v154
	v_add_u32_e32 v155, 0x80, v155
	v_add_u32_e32 v156, 0x80, v156
	v_add_u32_e32 v157, 0x80, v157
	v_add_u32_e32 v98, s28, v85
	v_add_u32_e32 v114, s28, v84
	v_add_u32_e32 v130, s28, v83
	v_add_u32_e32 v146, s28, v2
	ds_read_b128 v[86:89], v98
	ds_read_b128 v[90:93], v98 offset:2048
	ds_read_b128 v[94:97], v98 offset:4096
	ds_read_b128 v[98:101], v98 offset:6144
	ds_read_b128 v[102:105], v114 offset:16384
	ds_read_b128 v[106:109], v114 offset:18432
	ds_read_b128 v[110:113], v114 offset:20480
	ds_read_b128 v[114:117], v114 offset:22528
	ds_read_b128 v[118:121], v130
	ds_read_b128 v[122:125], v130 offset:2048
	ds_read_b128 v[126:129], v130 offset:4096
	ds_read_b128 v[130:133], v130 offset:6144
	ds_read_b128 v[134:137], v146 offset:16384
	ds_read_b128 v[138:141], v146 offset:18432
	ds_read_b128 v[142:145], v146 offset:20480
	ds_read_b128 v[146:149], v146 offset:22528
	s_setprio 1
	s_waitcnt lgkmcnt(0)
	v_mfma_f32_16x16x32_bf16 v[64:67], v[102:105], v[86:89], v[64:67]
	v_mfma_f32_16x16x32_bf16 v[60:63], v[106:109], v[86:89], v[60:63]
	v_mfma_f32_16x16x32_bf16 v[56:59], v[110:113], v[86:89], v[56:59]
	v_mfma_f32_16x16x32_bf16 v[52:55], v[114:117], v[86:89], v[52:55]
	v_mfma_f32_16x16x32_bf16 v[48:51], v[102:105], v[90:93], v[48:51]
	v_mfma_f32_16x16x32_bf16 v[44:47], v[106:109], v[90:93], v[44:47]
	v_mfma_f32_16x16x32_bf16 v[40:43], v[110:113], v[90:93], v[40:43]
	v_mfma_f32_16x16x32_bf16 v[36:39], v[114:117], v[90:93], v[36:39]
	v_mfma_f32_16x16x32_bf16 v[32:35], v[102:105], v[94:97], v[32:35]
	v_mfma_f32_16x16x32_bf16 v[28:31], v[106:109], v[94:97], v[28:31]
	v_mfma_f32_16x16x32_bf16 v[24:27], v[110:113], v[94:97], v[24:27]
	v_mfma_f32_16x16x32_bf16 v[20:23], v[114:117], v[94:97], v[20:23]
	v_mfma_f32_16x16x32_bf16 v[16:19], v[102:105], v[98:101], v[16:19]
	v_mfma_f32_16x16x32_bf16 v[12:15], v[106:109], v[98:101], v[12:15]
	v_mfma_f32_16x16x32_bf16 v[8:11], v[110:113], v[98:101], v[8:11]
	v_mfma_f32_16x16x32_bf16 v[4:7], v[114:117], v[98:101], v[4:7]
	v_mfma_f32_16x16x32_bf16 v[64:67], v[134:137], v[118:121], v[64:67]
	v_mfma_f32_16x16x32_bf16 v[60:63], v[138:141], v[118:121], v[60:63]
	v_mfma_f32_16x16x32_bf16 v[56:59], v[142:145], v[118:121], v[56:59]
	v_mfma_f32_16x16x32_bf16 v[52:55], v[146:149], v[118:121], v[52:55]
	v_mfma_f32_16x16x32_bf16 v[48:51], v[134:137], v[122:125], v[48:51]
	v_mfma_f32_16x16x32_bf16 v[44:47], v[138:141], v[122:125], v[44:47]
	v_mfma_f32_16x16x32_bf16 v[40:43], v[142:145], v[122:125], v[40:43]
	v_mfma_f32_16x16x32_bf16 v[36:39], v[146:149], v[122:125], v[36:39]
	v_mfma_f32_16x16x32_bf16 v[32:35], v[134:137], v[126:129], v[32:35]
	v_mfma_f32_16x16x32_bf16 v[28:31], v[138:141], v[126:129], v[28:31]
	v_mfma_f32_16x16x32_bf16 v[24:27], v[142:145], v[126:129], v[24:27]
	v_mfma_f32_16x16x32_bf16 v[20:23], v[146:149], v[126:129], v[20:23]
	v_mfma_f32_16x16x32_bf16 v[16:19], v[134:137], v[130:133], v[16:19]
	v_mfma_f32_16x16x32_bf16 v[12:15], v[138:141], v[130:133], v[12:15]
	v_mfma_f32_16x16x32_bf16 v[8:11], v[142:145], v[130:133], v[8:11]
	v_mfma_f32_16x16x32_bf16 v[4:7], v[146:149], v[130:133], v[4:7]
	s_setprio 0
	s_waitcnt vmcnt(0) lgkmcnt(0)
	s_add_u32 s26, s26, 0x80
	s_addc_u32 s27, s27, 0
	s_add_i32 s25, s25, 0x8000
	s_and_b32 s28, s25, 0x8000
	s_xor_b32 s29, s28, 0x8000
	s_add_i32 s29, s29, vcc_hi
	s_cmpk_eq_i32 s26, 0x780
	s_cbranch_scc0 .LBB0_657
	s_barrier
; __device__ __forceinline__ unsigned pk2(float lo, float hi) { unsigned r; asm("v_cvt_pk_bf16_f32 %0, %1, %2" : "=v"(r) : "v"(lo), "v"(hi)); return r; }
; __device__ __forceinline__ float bflo(unsigned u) { return __uint_as_float(u << 16); }
; __device__ __forceinline__ float bfhi(unsigned u) { return __uint_as_float(u & 0xffff0000u); }
; __device__ __forceinline__ void gemm_mainloop_d(const bf16_t* __restrict__ Ap, int lda, const bf16_t* __restrict__ Bt, int K,
;                                                 int m0, int n0, f32x4 (&acc)[4][4], char* lds) {
;     ...
;       for (int m = 0; m < 4; m++) { const int row = wr * 64 + m * 16 + fr; af[kc][m] = *(const bf16x8*)(la + (row * 8 + ((kc * 4 + fq) ^ ((row >> 1) & 7))) * 16); }
; #pragma unroll
;       for (int n = 0; n < 4; n++) { const int row = wc * 64 + n * 16 + fr; bfv[kc][n] = *(const bf16x8*)(lb + (row * 8 + ((kc * 4 + fq) ^ ((row >> 1) & 7))) * 16); }
;     }
;     __builtin_amdgcn_s_setprio(1);
; #pragma unroll
;     for (int kc = 0; kc < 2; kc++)
; #pragma unroll
;       for (int m = 0; m < 4; m++)
; #pragma unroll
;         for (int n = 0; n < 4; n++) acc[m][n] = __builtin_amdgcn_mfma_f32_16x16x32_bf16(bfv[kc][n], af[kc][m], acc[m][n], 0, 0, 0);
; __device__ __forceinline__ void gemm_A(const Params& p, int item, char* lds) {
;     ...
; #pragma unroll
;   for (int m = 0; m < 4; m++) {
;     const int rl = wr * 64 + m * 16 + fr; const float r = rsqrtf(rssg[rl] * (1.f / 1024.f) + 1e-6f);
;     float sq = 0.f;
; #pragma unroll
;     for (int n = 0; n < 4; n++) {
;       const int col = n0 + wc * 64 + n * 16 + fq * 4;
;       if (col < PIN) { f32x4 v = acc[m][n] * r; u32x2 w; w[0] = pk2(v[0], v[1]); w[1] = pk2(v[2], v[3]); *(u32x2*)(P + (size_t)(m0 + rl) * PIN + col) = w;
;         const float b0 = bflo(w[0]), b1 = bfhi(w[0]), b2 = bflo(w[1]), b3 = bfhi(w[1]); sq += b0 * b0 + b1 * b1 + b2 * b2 + b3 * b3; }
	v_add_u32_e32 v0, 0, v85
	ds_read_b128 v[68:71], v0 offset:32768
	ds_read_b128 v[72:75], v0 offset:34816
	ds_read_b128 v[76:79], v0 offset:36864
	ds_read_b128 v[86:89], v0 offset:38912
	v_add_u32_e32 v0, 0, v84
	ds_read_b128 v[90:93], v0 offset:49152
	ds_read_b128 v[94:97], v0 offset:51200
	ds_read_b128 v[98:101], v0 offset:53248
	ds_read_b128 v[102:105], v0 offset:55296
	v_add_u32_e32 v0, 0, v83
	ds_read_b128 v[80:83], v0 offset:32768
	ds_read_b128 v[106:109], v0 offset:34816
	ds_read_b128 v[110:113], v0 offset:36864
	ds_read_b128 v[114:117], v0 offset:38912
	v_add_u32_e32 v0, 0, v2
	ds_read_b128 v[118:121], v0 offset:49152
	ds_read_b128 v[122:125], v0 offset:51200
	ds_read_b128 v[126:129], v0 offset:53248
	ds_read_b128 v[130:133], v0 offset:55296
	s_setprio 1
	s_waitcnt lgkmcnt(0)
	v_mfma_f32_16x16x32_bf16 v[64:67], v[90:93], v[68:71], v[64:67]
	v_mfma_f32_16x16x32_bf16 v[60:63], v[94:97], v[68:71], v[60:63]
	v_mfma_f32_16x16x32_bf16 v[56:59], v[98:101], v[68:71], v[56:59]
	v_mfma_f32_16x16x32_bf16 v[52:55], v[102:105], v[68:71], v[52:55]
	v_mfma_f32_16x16x32_bf16 v[48:51], v[90:93], v[72:75], v[48:51]
	v_mfma_f32_16x16x32_bf16 v[44:47], v[94:97], v[72:75], v[44:47]
	v_mfma_f32_16x16x32_bf16 v[40:43], v[98:101], v[72:75], v[40:43]
	v_mfma_f32_16x16x32_bf16 v[36:39], v[102:105], v[72:75], v[36:39]
	v_mfma_f32_16x16x32_bf16 v[32:35], v[90:93], v[76:79], v[32:35]
	v_mfma_f32_16x16x32_bf16 v[28:31], v[94:97], v[76:79], v[28:31]
	v_mfma_f32_16x16x32_bf16 v[24:27], v[98:101], v[76:79], v[24:27]
	v_mfma_f32_16x16x32_bf16 v[20:23], v[102:105], v[76:79], v[20:23]
	v_mfma_f32_16x16x32_bf16 v[16:19], v[90:93], v[86:89], v[16:19]
	v_mfma_f32_16x16x32_bf16 v[12:15], v[94:97], v[86:89], v[12:15]
	v_mfma_f32_16x16x32_bf16 v[8:11], v[98:101], v[86:89], v[8:11]
	v_mfma_f32_16x16x32_bf16 v[4:7], v[102:105], v[86:89], v[4:7]
	v_mfma_f32_16x16x32_bf16 v[64:67], v[118:121], v[80:83], v[64:67]
	v_mfma_f32_16x16x32_bf16 v[60:63], v[122:125], v[80:83], v[60:63]
	v_mfma_f32_16x16x32_bf16 v[56:59], v[126:129], v[80:83], v[56:59]
	v_mfma_f32_16x16x32_bf16 v[52:55], v[130:133], v[80:83], v[52:55]
	v_mfma_f32_16x16x32_bf16 v[48:51], v[118:121], v[106:109], v[48:51]
	v_mfma_f32_16x16x32_bf16 v[44:47], v[122:125], v[106:109], v[44:47]
	v_mfma_f32_16x16x32_bf16 v[40:43], v[126:129], v[106:109], v[40:43]
	v_mfma_f32_16x16x32_bf16 v[36:39], v[130:133], v[106:109], v[36:39]
	v_mfma_f32_16x16x32_bf16 v[32:35], v[118:121], v[110:113], v[32:35]
	v_mfma_f32_16x16x32_bf16 v[28:31], v[122:125], v[110:113], v[28:31]
	v_mfma_f32_16x16x32_bf16 v[24:27], v[126:129], v[110:113], v[24:27]
	v_mfma_f32_16x16x32_bf16 v[20:23], v[130:133], v[110:113], v[20:23]
	v_mfma_f32_16x16x32_bf16 v[16:19], v[118:121], v[114:117], v[16:19]
	v_mfma_f32_16x16x32_bf16 v[12:15], v[122:125], v[114:117], v[12:15]
	v_mfma_f32_16x16x32_bf16 v[8:11], v[126:129], v[114:117], v[8:11]
	v_mfma_f32_16x16x32_bf16 v[4:7], v[130:133], v[114:117], v[4:7]
	s_setprio 0
	v_mov_b32_e32 v2, v198
	s_mov_b32 s25, s89
	s_waitcnt vmcnt(0) lgkmcnt(0)
	s_add_u32 s28, s46, s25
	s_addc_u32 s29, s47, 0
	s_ashr_i32 s25, s24, 31
	v_and_b32_e32 v0, 15, v2
	s_lshl_b64 s[26:27], s[24:25], 2
	v_ashrrev_i32_e32 v1, 1, v2
	s_movk_i32 s4, 0xffc0
	s_add_u32 s28, s28, s26
	v_and_or_b32 v0, v1, s4, v0
	s_addc_u32 s29, s29, s27
	v_ashrrev_i32_e32 v1, 31, v0
	v_lshl_add_u64 v[70:71], v[0:1], 2, s[28:29]
	s_mov_b32 s28, 0xff8c000
	v_add_co_u32_e32 v68, vcc, s28, v70
	s_mov_b32 s25, s89
	s_nop 0
	v_addc_co_u32_e32 v69, vcc, 0, v71, vcc
	global_load_dword v69, v[68:69], off
	v_and_b32_e32 v68, 64, v2
	v_bfe_u32 v2, v2, 4, 2
	v_lshlrev_b32_e32 v72, 2, v2
	v_or3_b32 v68, v72, v68, s3
	s_add_u32 s3, s46, s25
	s_addc_u32 s25, s47, 0
	s_add_u32 s30, s3, 0x768000
	s_addc_u32 s31, s25, 0
	v_add_u32_e32 v74, s24, v0
	v_mov_b32_e32 v76, 0
	v_cmp_gt_i32_e64 s[34:35], s78, v68
	s_waitcnt vmcnt(0)
	v_fmamk_f32 v69, v69, 0x3a800000, v200
	v_mul_f32_e32 v72, 0x4b800000, v69
	v_cmp_gt_f32_e32 vcc, s83, v69
	s_nop 1
	v_cndmask_b32_e32 v69, v69, v72, vcc
	v_rsq_f32_e32 v69, v69
	v_mov_b64_e32 v[72:73], s[30:31]
	v_mad_i64_i32 v[72:73], s[28:29], v74, s69, v[72:73]
	v_mul_f32_e32 v74, 0x45800000, v69
	v_cndmask_b32_e32 v74, v69, v74, vcc
	v_mov_b32_e32 v75, v74
	v_ashrrev_i32_e32 v69, 31, v68
	s_and_saveexec_b64 s[28:29], s[34:35]
	s_cbranch_execz .LBB0_660
	v_mov_b32_e32 v76, v74
	v_mov_b32_e32 v77, v74
	v_pk_mul_f32 v[66:67], v[66:67], v[76:77]
	v_pk_mul_f32 v[64:65], v[64:65], v[74:75]
	s_nop 0
	v_cvt_pk_bf16_f32 v64, v64, v65
	v_cvt_pk_bf16_f32 v65, v66, v67
	v_lshl_add_u64 v[66:67], v[68:69], 1, v[72:73]
	global_store_dwordx2 v[66:67], v[64:65], off
	v_lshlrev_b32_e32 v66, 16, v64
	v_and_b32_e32 v67, 0xffff0000, v64
	v_pk_mul_f32 v[66:67], v[66:67], v[66:67]
	v_and_b32_e32 v64, 0xffff0000, v65
	v_lshlrev_b32_e32 v65, 16, v65
	v_pk_mul_f32 v[64:65], v[64:65], v[64:65]
	v_add_f32_e32 v66, v66, v67
	v_add_f32_e32 v65, v66, v65
	v_add_f32_e32 v76, v64, v65
